# v23: NA attention loop hand-pipelined and unrolled (iterations 1-7), K/V tile prefetch two tiles deep with two staging register sets, bias gathers with immediate row offsets, NA units remapped so an X
# baseline (speedup 1.0000x reference)
.LBB0_274:
	v_mov_b32_e32 v0, v234
	s_lshr_b32 s39, s47, 2
	s_and_b32 s39, s39, 0x41
	s_mulk_i32 s39, 33
	s_and_b32 s39, s39, 0x60
	s_bfe_u32 s2, s47, 0x50003
	s_or_b32 s39, s39, s2
	v_readfirstlane_b32 s2, v0
	s_ashr_i32 s37, s47, 9
	s_bfe_u32 s36, s2, 0x20006
	s_ashr_i32 s2, s2, 3
	v_mov_b32_e32 v1, s2
	s_lshl_b32 s17, s37, 13
	s_lshl_b32 s2, s39, 6
	v_bfi_b32 v4, s73, v1, v0
	s_or_b32 s2, s2, s17
	s_and_b32 s34, s47, 3
	s_waitcnt vmcnt(19)
	v_add_u32_e32 v144, s2, v4
	v_ashrrev_i32_e32 v145, 31, v144
	s_lshl_b32 s38, s34, 8
	s_lshl_b32 s2, s36, 6
	v_lshlrev_b64 v[2:3], 12, v[144:145]
	s_or_b32 s2, s2, s38
	v_bfe_u32 v5, v0, 5, 1
	v_lshl_add_u64 v[2:3], s[18:19], 0, v[2:3]
	s_lshl_b32 s70, s2, 1
	v_lshl_add_u64 v[2:3], v[2:3], 0, s[70:71]
	v_lshlrev_b32_e32 v146, 4, v5
	v_mov_b32_e32 v147, v201
	v_lshl_add_u64 v[2:3], v[2:3], 0, v[146:147]
	global_load_dwordx4 v[96:99], v[2:3], off
	global_load_dwordx4 v[100:103], v[2:3], off offset:32
	global_load_dwordx4 v[104:107], v[2:3], off offset:64
	global_load_dwordx4 v[108:111], v[2:3], off offset:96
	s_movk_i32 s2, 0x744
	s_and_b32 s16, s22, 3
	v_cmp_gt_i32_e32 vcc, s2, v0
	v_readlane_b32 s4, v255, 4
	s_xor_b32 s4, s4, s47
	s_cmp_eq_u32 s4, 0
	s_cbranch_scc1 .Lna_loadbias
	s_and_b32 s4, s4, 3
	s_cmp_eq_u32 s4, 0
	s_cbranch_scc1 .Lna_skipbias

.Lna_skipbias:
	v_med3_u32 v1, s39, 4, v241
	v_lshlrev_b32_e32 v2, 4, v0
	v_lshlrev_b32_e32 v1, 6, v1
	v_and_b32_e32 v200, 0x70, v2
	v_add_u32_e32 v2, 0xffffff00, v1
	v_ashrrev_i32_e32 v10, 3, v0
	v_add_u32_e32 v1, s17, v2
	v_add_u32_e32 v6, v1, v10
	v_ashrrev_i32_e32 v7, 31, v6
	v_lshlrev_b64 v[6:7], 12, v[6:7]
	v_lshl_add_u64 v[6:7], s[18:19], 0, v[6:7]
	s_lshl_b32 s2, s38, 1
	s_mov_b32 s3, s71
	s_lshl_b32 s6, s37, 10
	v_lshl_add_u64 v[6:7], v[6:7], 0, s[2:3]
	s_or_b32 s2, s6, s38
	v_add_u32_e32 v8, s2, v10
	v_ashrrev_i32_e32 v9, 31, v8
	v_lshlrev_b64 v[8:9], 14, v[8:9]
	v_lshl_add_u64 v[8:9], s[68:69], 0, v[8:9]
	v_mov_b32_e32 v3, v201
	v_lshl_add_u64 v[2:3], v[2:3], 1, v[8:9]
	v_lshl_add_u64 v[2:3], v[2:3], 0, v[200:201]
	v_add_co_u32_e32 v8, vcc, s72, v2
	s_mov_b32 s2, 0x200000
	s_nop 0
	v_addc_co_u32_e32 v9, vcc, 0, v3, vcc
	global_load_dwordx4 v[112:115], v[2:3], off
	global_load_dwordx4 v[116:119], v[8:9], off
	v_add_co_u32_e32 v8, vcc, s2, v2
	s_mov_b32 s2, 0x300000
	s_nop 0
	v_addc_co_u32_e32 v9, vcc, 0, v3, vcc
	v_add_co_u32_e32 v2, vcc, s2, v2
	v_lshl_add_u64 v[6:7], v[6:7], 0, v[200:201]
	s_nop 0
	v_addc_co_u32_e32 v3, vcc, 0, v3, vcc
	global_load_dwordx4 v[132:135], v[8:9], off
	global_load_dwordx4 v[140:143], v[2:3], off
	global_load_dwordx4 v[120:123], v[6:7], off offset:2048
	global_load_dwordx4 v[124:127], v[6:7], off offset:2176
	global_load_dwordx4 v[128:131], v[6:7], off offset:2304
	global_load_dwordx4 v[136:139], v[6:7], off offset:2432
	v_and_b32_e32 v3, 31, v0
	v_and_b32_e32 v2, 19, v0
	v_lshrrev_b32_e32 v0, 1, v0
	v_mul_lo_u32 v6, v10, s24
	v_lshlrev_b32_e32 v7, 1, v3
	s_waitcnt vmcnt(30)
	v_lshlrev_b32_e32 v148, 3, v5
	v_med3_i32 v5, v4, 8, 56
	v_and_b32_e32 v0, 4, v0
	v_add3_u32 v147, v6, v200, 0
	v_and_b32_e32 v6, 8, v7
	v_sub_u32_e32 v5, v148, v5
	v_or3_b32 v2, v2, v6, v0
	v_mul_u32_u24_e32 v149, 0x90, v2
	v_add_u32_e32 v2, 10, v5
	v_cmp_gt_u32_e64 s[52:53], 16, v2
	v_add_u32_e32 v2, 11, v5
	v_cmp_gt_u32_e64 s[54:55], 16, v2
	v_add_u32_e32 v2, 12, v5
	v_cmp_gt_u32_e64 s[56:57], 16, v2
	v_add_u32_e32 v2, 13, v5
	v_cmp_gt_u32_e64 s[58:59], 16, v2
	v_add_u32_e32 v2, 14, v5
	v_cmp_gt_u32_e64 s[60:61], 16, v2
	v_add_u32_e32 v2, 15, v5
	v_cmp_gt_u32_e64 s[62:63], 16, v2
	v_add_u32_e32 v2, 25, v5
	v_add_u32_e32 v6, 41, v5
	v_cmp_gt_u32_e64 s[66:67], 16, v2
	v_add_u32_e32 v2, 26, v5
	v_cmp_gt_u32_e64 s[82:83], 16, v6
	v_add_u32_e32 v6, 42, v5
	s_mov_b64 s[14:15], s[68:69]
	v_cmp_gt_u32_e64 s[68:69], 16, v2
	v_add_u32_e32 v2, 27, v5
	v_cmp_gt_u32_e64 s[84:85], 16, v6
	v_add_u32_e32 v6, 43, v5
	s_mov_b64 s[0:1], s[70:71]
	s_lshr_b32 s2, s47, 2
	v_cmp_gt_u32_e64 s[70:71], 16, v2
	v_add_u32_e32 v2, 28, v5
	v_cmp_gt_u32_e64 s[86:87], 16, v6
	v_add_u32_e32 v6, 44, v5
	s_and_b32 s35, s2, 0x41
	s_bfe_u32 s2, s2, 0x50001
	s_mulk_i32 s35, 33
	s_and_b32 s35, s35, 0x60
	s_or_b32 s35, s35, s2
	v_cmp_gt_u32_e64 s[72:73], 16, v2
	v_add_u32_e32 v2, 29, v5
	v_cmp_gt_u32_e64 s[88:89], 16, v6
	v_add_u32_e32 v6, 45, v5
	v_sub_u32_e32 v4, v148, v4
	v_med3_u32 v8, s35, 4, v241
	v_cmp_gt_u32_e64 s[74:75], 16, v2
	v_add_u32_e32 v2, 30, v5
	v_cmp_gt_u32_e64 s[90:91], 16, v6
	v_add_u32_e32 v6, 46, v5
	s_mul_i32 s3, s36, 0x4800
	v_add_u32_e32 v7, 8, v5
	v_add_u32_e32 v4, 15, v4
	v_add_u32_e32 v9, 9, v5
	s_movk_i32 s2, 0x7c
	v_lshlrev_b32_e32 v12, 7, v8
	s_movk_i32 s4, 0xffef
	v_cmp_gt_u32_e64 s[76:77], 16, v2
	v_add_u32_e32 v2, 31, v5
	v_cmp_gt_u32_e64 s[92:93], 16, v6
	v_add_u32_e32 v6, 47, v5
	s_add_i32 s37, s3, 0
	v_mul_lo_u32 v11, v8, s2
	v_cmp_gt_u32_e64 s[2:3], 16, v7
	v_add_u32_e32 v0, 0xfffffe00, v12
	v_cmp_gt_u32_e64 s[48:49], 16, v9
	v_cmp_lt_u32_e64 s[64:65], s4, v7
	v_cmp_gt_u32_e64 s[78:79], 16, v2
	v_and_b32_e32 v2, -16, v7
	s_movk_i32 s4, 0xffe0
	v_cmp_gt_u32_e64 s[94:95], 16, v6
	v_med3_i32 v6, v4, 0, 30
	v_max_i32_e32 v7, -1, v4
	v_max_i32_e32 v9, -2, v4
	v_max_i32_e32 v12, -3, v4
	v_max_i32_e32 v13, -4, v4
	v_max_i32_e32 v14, -5, v4
	v_max_i32_e32 v15, -6, v4
	v_max_i32_e32 v16, -7, v4
	v_max_i32_e32 v17, -16, v4
	v_max_i32_e32 v18, 0xffffffef, v4
	v_max_i32_e32 v19, 0xffffffee, v4
	v_max_i32_e32 v20, 0xffffffed, v4
	v_max_i32_e32 v21, 0xffffffec, v4
	v_max_i32_e32 v22, 0xffffffeb, v4
	v_max_i32_e32 v23, 0xffffffea, v4
	v_max_i32_e32 v24, 0xffffffe9, v4
	v_max_i32_e32 v25, 0xffffffe0, v4
	v_max_i32_e32 v26, 0xffffffdf, v4
	v_max_i32_e32 v27, 0xffffffde, v4
	v_max_i32_e32 v28, 0xffffffdd, v4
	v_max_i32_e32 v29, 0xffffffdc, v4
	v_max_i32_e32 v30, 0xffffffdb, v4
	v_max_i32_e32 v31, 0xffffffda, v4
	v_max_i32_e32 v32, 0xffffffd9, v4
	v_max_i32_e32 v33, 0xffffffd0, v4
	v_max_i32_e32 v34, 0xffffffcf, v4
	v_max_i32_e32 v35, 0xffffffce, v4
	v_max_i32_e32 v36, 0xffffffcd, v4
	v_max_i32_e32 v37, 0xffffffcc, v4
	v_max_i32_e32 v38, 0xffffffcb, v4
	v_max_i32_e32 v39, 0xffffffca, v4
	v_max_i32_e32 v4, 0xffffffc9, v4
	v_cmp_eq_u32_e64 s[80:81], s4, v2
	s_movk_i32 s4, 0xffd0
	v_add_u32_e32 v4, 55, v4
	s_mulk_i32 s36, 0x744
	v_cmp_eq_u32_e64 s[96:97], s4, v2
	v_add_u32_e32 v2, 57, v5
	v_add_u32_e32 v7, 1, v7
	v_add_u32_e32 v9, 2, v9
	v_add_u32_e32 v12, 3, v12
	v_add_u32_e32 v13, 4, v13
	v_add_u32_e32 v14, 5, v14
	v_add_u32_e32 v15, 6, v15
	v_add_u32_e32 v16, 7, v16
	v_add_u32_e32 v17, 16, v17
	v_add_u32_e32 v18, 17, v18
	v_add_u32_e32 v19, 18, v19
	v_add_u32_e32 v20, 19, v20
	v_add_u32_e32 v21, 20, v21
	v_add_u32_e32 v22, 21, v22
	v_add_u32_e32 v23, 22, v23
	v_add_u32_e32 v24, 23, v24
	v_add_u32_e32 v25, 32, v25
	v_add_u32_e32 v26, 33, v26
	v_add_u32_e32 v27, 34, v27
	v_add_u32_e32 v28, 35, v28
	v_add_u32_e32 v29, 36, v29
	v_add_u32_e32 v30, 37, v30
	v_add_u32_e32 v31, 38, v31
	v_add_u32_e32 v32, 39, v32
	v_add_u32_e32 v33, 48, v33
	v_add_u32_e32 v34, 49, v34
	v_add_u32_e32 v35, 50, v35
	v_add_u32_e32 v36, 51, v36
	v_add_u32_e32 v37, 52, v37
	v_add_u32_e32 v38, 53, v38
	v_add_u32_e32 v39, 54, v39
	v_min_u32_e32 v4, 30, v4
	v_add_u32_e32 v11, s36, v11
	s_mulk_i32 s35, 0x7c
	v_cmp_gt_u32_e64 s[40:41], 16, v2
	v_add_u32_e32 v2, 58, v5
	v_min_u32_e32 v7, 30, v7
	v_min_u32_e32 v9, 30, v9
	v_min_u32_e32 v12, 30, v12
	v_min_u32_e32 v13, 30, v13
	v_min_u32_e32 v14, 30, v14
	v_min_u32_e32 v15, 30, v15
	v_min_u32_e32 v16, 30, v16
	v_min_u32_e32 v17, 30, v17
	v_min_u32_e32 v18, 30, v18
	v_min_u32_e32 v19, 30, v19
	v_min_u32_e32 v20, 30, v20
	v_min_u32_e32 v21, 30, v21
	v_min_u32_e32 v22, 30, v22
	v_min_u32_e32 v23, 30, v23
	v_min_u32_e32 v24, 30, v24
	v_min_u32_e32 v25, 30, v25
	v_min_u32_e32 v26, 30, v26
	v_min_u32_e32 v27, 30, v27
	v_min_u32_e32 v28, 30, v28
	v_min_u32_e32 v29, 30, v29
	v_min_u32_e32 v30, 30, v30
	v_min_u32_e32 v31, 30, v31
	v_min_u32_e32 v32, 30, v32
	v_min_u32_e32 v33, 30, v33
	v_min_u32_e32 v34, 30, v34
	v_min_u32_e32 v35, 30, v35
	v_min_u32_e32 v36, 30, v36
	v_min_u32_e32 v37, 30, v37
	v_min_u32_e32 v38, 30, v38
	v_min_u32_e32 v39, 30, v39
	v_lshl_add_u32 v4, v4, 2, v11
	v_lshlrev_b32_e32 v8, 6, v8
	v_cmp_gt_u32_e64 s[38:39], 16, v2
	v_add_u32_e32 v2, 59, v5
	v_lshl_add_u32 v6, v6, 2, v11
	v_lshl_add_u32 v7, v7, 2, v11
	v_lshl_add_u32 v9, v9, 2, v11
	v_lshl_add_u32 v12, v12, 2, v11
	v_lshl_add_u32 v13, v13, 2, v11
	v_lshl_add_u32 v14, v14, 2, v11
	v_lshl_add_u32 v15, v15, 2, v11
	v_lshl_add_u32 v16, v16, 2, v11
	v_lshl_add_u32 v17, v17, 2, v11
	v_lshl_add_u32 v18, v18, 2, v11
	v_lshl_add_u32 v19, v19, 2, v11
	v_lshl_add_u32 v20, v20, 2, v11
	v_lshl_add_u32 v21, v21, 2, v11
	v_lshl_add_u32 v22, v22, 2, v11
	v_lshl_add_u32 v23, v23, 2, v11
	v_lshl_add_u32 v24, v24, 2, v11
	v_lshl_add_u32 v25, v25, 2, v11
	v_lshl_add_u32 v26, v26, 2, v11
	v_lshl_add_u32 v27, v27, 2, v11
	v_lshl_add_u32 v28, v28, 2, v11
	v_lshl_add_u32 v29, v29, 2, v11
	v_lshl_add_u32 v30, v30, 2, v11
	v_lshl_add_u32 v31, v31, 2, v11
	v_lshl_add_u32 v32, v32, 2, v11
	v_lshl_add_u32 v33, v33, 2, v11
	v_lshl_add_u32 v34, v34, 2, v11
	v_lshl_add_u32 v35, v35, 2, v11
	v_lshl_add_u32 v36, v36, 2, v11
	v_lshl_add_u32 v37, v37, 2, v11
	v_lshl_add_u32 v38, v38, 2, v11
	v_lshl_add_u32 v39, v39, 2, v11
	v_subrev_u32_e32 v11, s35, v4
	v_add_u32_e32 v4, 62, v5
	s_lshl_b32 s34, s16, 8
	v_cmp_gt_u32_e64 s[44:45], 16, v2
	v_add_u32_e32 v2, 60, v5
	v_cmp_gt_u32_e64 s[50:51], 16, v4
	v_add_u32_e32 v4, s17, v8
	v_cmp_gt_u32_e64 s[4:5], 16, v2
	v_add_u32_e32 v2, 61, v5
	s_or_b32 s6, s34, s6
	v_add_u32_e32 v4, v10, v4
	s_lshl_b32 s7, s16, 9
	v_cmp_gt_u32_e64 s[42:43], 16, v2
	v_add_u32_e32 v2, s6, v10
	v_add_u32_e32 v4, 0xffffff00, v4
	v_readlane_b32 s6, v254, 49
	v_add_u32_e32 v40, 63, v5
	v_ashrrev_i32_e32 v5, 31, v4
	s_add_u32 s6, s6, s7
	v_readlane_b32 s7, v254, 50
	v_mov_b32_e32 v1, v201
	v_subrev_u32_e32 v32, s35, v32
	v_subrev_u32_e32 v33, s35, v33
	v_subrev_u32_e32 v34, s35, v34
	v_subrev_u32_e32 v35, s35, v35
	v_subrev_u32_e32 v36, s35, v36
	v_subrev_u32_e32 v37, s35, v37
	v_subrev_u32_e32 v38, s35, v38
	v_subrev_u32_e32 v39, s35, v39
	v_lshlrev_b64 v[4:5], 12, v[4:5]
	s_addc_u32 s7, s7, 0
	s_waitcnt vmcnt(29)
	v_mul_u32_u24_e32 v154, 0x90, v3
	v_ashrrev_i32_e32 v3, 31, v2
	v_mov_b32_e32 v46, v201
	v_mov_b32_e32 v47, v201
	v_subrev_u32_e32 v6, s35, v6
	v_subrev_u32_e32 v7, s35, v7
	v_subrev_u32_e32 v9, s35, v9
	v_subrev_u32_e32 v12, s35, v12
	v_subrev_u32_e32 v13, s35, v13
	v_subrev_u32_e32 v14, s35, v14
	v_subrev_u32_e32 v15, s35, v15
	v_subrev_u32_e32 v16, s35, v16
	v_subrev_u32_e32 v17, s35, v17
	v_subrev_u32_e32 v18, s35, v18
	v_subrev_u32_e32 v19, s35, v19
	v_subrev_u32_e32 v20, s35, v20
	v_subrev_u32_e32 v21, s35, v21
	v_subrev_u32_e32 v22, s35, v22
	v_subrev_u32_e32 v23, s35, v23
	v_subrev_u32_e32 v24, s35, v24
	v_subrev_u32_e32 v25, s35, v25
	v_subrev_u32_e32 v26, s35, v26
	v_subrev_u32_e32 v27, s35, v27
	v_subrev_u32_e32 v28, s35, v28
	v_subrev_u32_e32 v29, s35, v29
	v_subrev_u32_e32 v30, s35, v30
	v_subrev_u32_e32 v31, s35, v31
	v_lshl_add_u64 v[150:151], s[6:7], 0, v[4:5]
	v_cmp_gt_u32_e64 s[6:7], 16, v40
	v_add_u32_e32 v178, s23, v32
	v_add_u32_e32 v179, s23, v33
	v_add_u32_e32 v180, s23, v34
	v_add_u32_e32 v181, s23, v35
	v_add_u32_e32 v182, s23, v36
	v_add_u32_e32 v183, s23, v37
	v_add_u32_e32 v184, s23, v38
	v_add_u32_e32 v185, s23, v39
	v_lshlrev_b64 v[2:3], 14, v[2:3]
	v_lshl_add_u64 v[0:1], s[10:11], 0, v[0:1]
	v_mov_b32_e32 v32, v201
	v_mov_b32_e32 v33, v201
	v_mov_b32_e32 v34, v201
	v_mov_b32_e32 v35, v201
	v_mov_b32_e32 v36, v201
	v_mov_b32_e32 v37, v201
	v_mov_b32_e32 v38, v201
	v_mov_b32_e32 v39, v201
	v_mov_b32_e32 v40, v201
	v_mov_b32_e32 v41, v201
	v_mov_b32_e32 v42, v201
	v_mov_b32_e32 v43, v201
	v_mov_b32_e32 v44, v201
	v_mov_b32_e32 v45, v201
	v_mov_b32_e32 v187, 0
	v_mov_b64_e32 v[62:63], v[46:47]
	s_mov_b32 s16, 0
	v_add_u32_e32 v155, s23, v6
	s_waitcnt vmcnt(28)
	v_add_u32_e32 v156, s23, v7
	v_add_u32_e32 v157, s23, v9
	v_add_u32_e32 v158, s23, v12
	v_add_u32_e32 v159, s23, v13
	v_add_u32_e32 v160, s23, v14
	v_add_u32_e32 v161, s23, v15
	v_add_u32_e32 v162, s23, v16
	v_add_u32_e32 v163, s23, v17
	v_add_u32_e32 v164, s23, v18
	v_add_u32_e32 v165, s23, v19
	v_add_u32_e32 v166, s23, v20
	v_add_u32_e32 v167, s23, v21
	v_add_u32_e32 v168, s23, v22
	v_add_u32_e32 v169, s23, v23
	v_add_u32_e32 v170, s23, v24
	v_add_u32_e32 v171, s23, v25
	v_add_u32_e32 v172, s23, v26
	v_add_u32_e32 v173, s23, v27
	v_add_u32_e32 v174, s23, v28
	v_add_u32_e32 v175, s23, v29
	v_add_u32_e32 v176, s23, v30
	v_add_u32_e32 v177, s23, v31
	v_add_u32_e32 v186, s23, v11
	v_lshl_add_u64 v[152:153], v[0:1], 0, v[2:3]
	v_mov_b64_e32 v[60:61], v[44:45]
	v_mov_b64_e32 v[58:59], v[42:43]
	v_mov_b64_e32 v[56:57], v[40:41]
	v_mov_b64_e32 v[54:55], v[38:39]
	v_mov_b64_e32 v[52:53], v[36:37]
	v_mov_b64_e32 v[50:51], v[34:35]
	v_mov_b64_e32 v[48:49], v[32:33]
	v_mov_b32_e32 v188, 0
	v_mov_b32_e32 v64, 0
	v_mov_b32_e32 v65, v187
	v_mov_b32_e32 v66, v187
	v_mov_b32_e32 v67, v187
	v_mov_b32_e32 v68, v187
	v_mov_b32_e32 v69, v187
	v_mov_b32_e32 v70, v187
	v_mov_b32_e32 v71, v187
	v_mov_b32_e32 v72, v187
	v_mov_b32_e32 v73, v187
	v_mov_b32_e32 v74, v187
	v_mov_b32_e32 v75, v187
	v_mov_b32_e32 v76, v187
	v_mov_b32_e32 v77, v187
	v_mov_b32_e32 v78, v187
	v_mov_b32_e32 v79, v187
	s_mov_b32 s36, 0
	s_waitcnt vmcnt(7)
	ds_write_b128 v147, v[112:115] offset:9216
	s_waitcnt vmcnt(6)
	ds_write_b128 v147, v[116:119] offset:27648
	s_waitcnt vmcnt(5)
	ds_write_b128 v147, v[132:135] offset:46080
	s_waitcnt vmcnt(4)
	ds_write_b128 v147, v[140:143] offset:64512
	s_waitcnt vmcnt(3)
	ds_write_b128 v147, v[120:123]
	s_waitcnt vmcnt(2)
	ds_write_b128 v147, v[124:127] offset:18432
	s_waitcnt vmcnt(1)
	ds_write_b128 v147, v[128:131] offset:36864
	s_waitcnt vmcnt(0)
	ds_write_b128 v147, v[136:139] offset:55296
	s_waitcnt lgkmcnt(0)
	s_barrier
	s_branch .LBB0_284

.LBB0_284:
	s_cmp_lg_u32 s16, 0
	s_cbranch_scc1 .Lna_loop
	s_cmpk_lg_i32 s16, 0x364
	s_cselect_b64 s[34:35], -1, 0
	s_cmpk_eq_i32 s16, 0x364
	s_cbranch_scc1 .LBB0_286
	v_lshl_add_u64 v[2:3], v[152:153], 0, v[200:201]
	v_add_co_u32_e32 v4, vcc, 0x12d00000, v2
	v_lshl_add_u64 v[0:1], v[150:151], 0, v[200:201]
	s_nop 0
	v_addc_co_u32_e32 v5, vcc, 0, v3, vcc
	v_add_co_u32_e32 v6, vcc, 0x12e00000, v2
	global_load_dwordx4 v[120:123], v[0:1], off offset:-256
	global_load_dwordx4 v[124:127], v[0:1], off offset:-128
	v_addc_co_u32_e32 v7, vcc, 0, v3, vcc
	global_load_dwordx4 v[112:115], v[4:5], off offset:128
	global_load_dwordx4 v[116:119], v[6:7], off offset:128
	v_add_co_u32_e32 v4, vcc, 0x12f00000, v2
	global_load_dwordx4 v[128:131], v[0:1], off
	global_load_dwordx4 v[136:139], v[0:1], off offset:128
	v_addc_co_u32_e32 v5, vcc, 0, v3, vcc
	v_add_co_u32_e32 v0, vcc, 0x13000000, v2
	s_nop 1
	v_addc_co_u32_e32 v1, vcc, 0, v3, vcc
	global_load_dwordx4 v[132:135], v[4:5], off offset:128
	global_load_dwordx4 v[140:143], v[0:1], off offset:128

.Lna_loop:
.Lna_it1:
	s_add_i32 s17, s37, 0x12000
	v_add3_u32 v248, s17, v146, v149
	v_add3_u32 v249, s17, v154, v146
	ds_read_b128 v[204:207], v248
	ds_read_b128 v[208:211], v248 offset:32
	ds_read_b128 v[212:215], v248 offset:64
	ds_read_b128 v[216:219], v248 offset:96
	v_lshl_add_u64 v[2:3], v[152:153], 0, v[200:201]
	v_add_co_u32_e32 v4, vcc, 0x12d00000, v2
	v_lshl_add_u64 v[0:1], v[150:151], 0, v[200:201]
	s_nop 0
	v_addc_co_u32_e32 v5, vcc, 0, v3, vcc
	v_add_co_u32_e32 v6, vcc, 0x12e00000, v2
	global_load_dwordx4 v[120:123], v[0:1], off offset:-256
	global_load_dwordx4 v[124:127], v[0:1], off offset:-128
	v_addc_co_u32_e32 v7, vcc, 0, v3, vcc
	global_load_dwordx4 v[112:115], v[4:5], off offset:128
	global_load_dwordx4 v[116:119], v[6:7], off offset:128
	v_add_co_u32_e32 v4, vcc, 0x12f00000, v2
	global_load_dwordx4 v[128:131], v[0:1], off
	global_load_dwordx4 v[136:139], v[0:1], off offset:128
	v_addc_co_u32_e32 v5, vcc, 0, v3, vcc
	v_add_co_u32_e32 v0, vcc, 0x13000000, v2
	s_nop 1
	v_addc_co_u32_e32 v1, vcc, 0, v3, vcc
	global_load_dwordx4 v[132:135], v[4:5], off offset:128
	global_load_dwordx4 v[140:143], v[0:1], off offset:128
	v_lshl_add_u64 v[152:153], v[152:153], 0, s[26:27]
	v_lshl_add_u64 v[150:151], v[150:151], 0, s[28:29]
	v_lshl_add_u64 v[2:3], v[152:153], 0, v[200:201]
	v_add_co_u32_e32 v4, vcc, 0x12d00000, v2
	v_lshl_add_u64 v[0:1], v[150:151], 0, v[200:201]
	s_nop 0
	v_addc_co_u32_e32 v5, vcc, 0, v3, vcc
	v_add_co_u32_e32 v6, vcc, 0x12e00000, v2
	global_load_dwordx4 v[80:83], v[0:1], off offset:-256
	global_load_dwordx4 v[84:87], v[0:1], off offset:-128
	v_addc_co_u32_e32 v7, vcc, 0, v3, vcc
	global_load_dwordx4 v[88:91], v[4:5], off offset:128
	global_load_dwordx4 v[92:95], v[6:7], off offset:128
	v_add_co_u32_e32 v4, vcc, 0x12f00000, v2
	global_load_dwordx4 v[220:223], v[0:1], off
	global_load_dwordx4 v[224:227], v[0:1], off offset:128
	v_addc_co_u32_e32 v5, vcc, 0, v3, vcc
	v_add_co_u32_e32 v0, vcc, 0x13000000, v2
	s_nop 1
	v_addc_co_u32_e32 v1, vcc, 0, v3, vcc
	global_load_dwordx4 v[228:231], v[4:5], off offset:128
	global_load_dwordx4 v[244:247], v[0:1], off offset:128
	v_lshl_add_u64 v[152:153], v[152:153], 0, s[26:27]
	v_lshl_add_u64 v[150:151], v[150:151], 0, s[28:29]
	v_mov_b32_e32 v203, 0xf149f2ca
	ds_read_b32 v189, v155 offset:124
	ds_read_b32 v190, v156 offset:124
	ds_read_b32 v191, v157 offset:124
	ds_read_b32 v192, v158 offset:124
	ds_read_b32 v193, v159 offset:124
	ds_read_b32 v194, v160 offset:124
	ds_read_b32 v195, v161 offset:124
	ds_read_b32 v196, v162 offset:124
	ds_read_b32 v197, v163 offset:124
	ds_read_b32 v198, v164 offset:124
	ds_read_b32 v199, v165 offset:124
	s_waitcnt lgkmcnt(14)
	v_mfma_f32_32x32x16_bf16 v[0:15], v[204:207], v[96:99], v[64:79]
	s_waitcnt lgkmcnt(13)
	v_mfma_f32_32x32x16_bf16 v[0:15], v[208:211], v[100:103], v[0:15]
	s_waitcnt lgkmcnt(12)
	v_mfma_f32_32x32x16_bf16 v[0:15], v[212:215], v[104:107], v[0:15]
	s_waitcnt lgkmcnt(11)
	v_mfma_f32_32x32x16_bf16 v[0:15], v[216:219], v[108:111], v[0:15]
	ds_read_b128 v[204:207], v248 offset:4608
	ds_read_b128 v[208:211], v248 offset:4640
	ds_read_b128 v[212:215], v248 offset:4672
	ds_read_b128 v[216:219], v248 offset:4704
	s_waitcnt lgkmcnt(3)
	v_mfma_f32_32x32x16_bf16 v[16:31], v[204:207], v[96:99], v[64:79]
	s_nop 5
	v_add_f32_e32 v0, v0, v189
	v_cndmask_b32_e64 v0, v203, v0, s[2:3]
	ds_read_b32 v189, v166 offset:124
	v_add_f32_e32 v1, v1, v190
	v_cndmask_b32_e64 v1, v203, v1, s[48:49]
	ds_read_b32 v190, v167 offset:124
	s_waitcnt lgkmcnt(4)
	v_mfma_f32_32x32x16_bf16 v[16:31], v[208:211], v[100:103], v[16:31]
	v_add_f32_e32 v2, v2, v191
	v_cndmask_b32_e64 v2, v203, v2, s[52:53]
	ds_read_b32 v191, v168 offset:124
	v_add_f32_e32 v3, v3, v192
	v_cndmask_b32_e64 v3, v203, v3, s[54:55]
	ds_read_b32 v192, v169 offset:124
	s_waitcnt lgkmcnt(5)
	v_mfma_f32_32x32x16_bf16 v[16:31], v[212:215], v[104:107], v[16:31]
	v_add_f32_e32 v4, v4, v193
	v_cndmask_b32_e64 v4, v203, v4, s[56:57]
	ds_read_b32 v193, v170 offset:124
	v_add_f32_e32 v5, v5, v194
	v_cndmask_b32_e64 v5, v203, v5, s[58:59]
	ds_read_b32 v194, v171 offset:124
	s_waitcnt lgkmcnt(6)
	v_mfma_f32_32x32x16_bf16 v[16:31], v[216:219], v[108:111], v[16:31]
	ds_read_b128 v[204:207], v249 offset:9216
	ds_read_b128 v[208:211], v249 offset:13824
	ds_read_b128 v[212:215], v249 offset:9248
	ds_read_b128 v[216:219], v249 offset:13856
	v_add_f32_e32 v6, v6, v195
	v_cndmask_b32_e64 v6, v203, v6, s[60:61]
	ds_read_b32 v195, v172 offset:124
	v_add_f32_e32 v7, v7, v196
	v_cndmask_b32_e64 v7, v203, v7, s[62:63]
	ds_read_b32 v196, v173 offset:124
	v_exp_f32_e32 v0, v0
	v_exp_f32_e32 v1, v1
	v_exp_f32_e32 v2, v2
	v_exp_f32_e32 v3, v3
	v_add_f32_e32 v232, v0, v2
	v_add_f32_e32 v233, v1, v3
	v_exp_f32_e32 v4, v4
	v_exp_f32_e32 v5, v5
	v_add_f32_e32 v232, v232, v4
	v_add_f32_e32 v233, v233, v5
	v_exp_f32_e32 v6, v6
	v_exp_f32_e32 v7, v7
	v_add_f32_e32 v232, v232, v6
	v_add_f32_e32 v233, v233, v7
	v_cvt_pk_bf16_f32 v0, v0, v1
	v_cvt_pk_bf16_f32 v1, v2, v3
	v_cvt_pk_bf16_f32 v2, v4, v5
	v_cvt_pk_bf16_f32 v3, v6, v7
	s_waitcnt lgkmcnt(5)
	s_nop 0
	v_mfma_f32_32x32x16_bf16 v[48:63], v[204:207], v[0:3], v[48:63]
	s_waitcnt lgkmcnt(4)
	v_mfma_f32_32x32x16_bf16 v[32:47], v[208:211], v[0:3], v[32:47]
	v_add_f32_e32 v8, v8, v197
	v_cndmask_b32_e64 v8, v203, v8, s[64:65]
	ds_read_b32 v197, v174 offset:124
	v_add_f32_e32 v9, v9, v198
	v_cndmask_b32_e64 v9, v203, v9, s[66:67]
	ds_read_b32 v198, v175 offset:124
	v_add_f32_e32 v10, v10, v199
	v_cndmask_b32_e64 v10, v203, v10, s[68:69]
	ds_read_b32 v199, v176 offset:124
	v_add_f32_e32 v11, v11, v189
	v_cndmask_b32_e64 v11, v203, v11, s[70:71]
	ds_read_b32 v189, v177 offset:124
	v_add_f32_e32 v12, v12, v190
	v_cndmask_b32_e64 v12, v203, v12, s[72:73]
	ds_read_b32 v190, v178 offset:124
	v_add_f32_e32 v13, v13, v191
	v_cndmask_b32_e64 v13, v203, v13, s[74:75]
	ds_read_b32 v191, v179 offset:124
	v_add_f32_e32 v14, v14, v192
	v_cndmask_b32_e64 v14, v203, v14, s[76:77]
	ds_read_b32 v192, v180 offset:124
	v_add_f32_e32 v15, v15, v193
	v_cndmask_b32_e64 v15, v203, v15, s[78:79]
	ds_read_b32 v193, v181 offset:124
	v_exp_f32_e32 v8, v8
	v_exp_f32_e32 v9, v9
	v_add_f32_e32 v232, v232, v8
	v_add_f32_e32 v233, v233, v9
	v_exp_f32_e32 v10, v10
	v_exp_f32_e32 v11, v11
	v_add_f32_e32 v232, v232, v10
	v_add_f32_e32 v233, v233, v11
	v_exp_f32_e32 v12, v12
	v_exp_f32_e32 v13, v13
	v_add_f32_e32 v232, v232, v12
	v_add_f32_e32 v233, v233, v13
	v_exp_f32_e32 v14, v14
	v_exp_f32_e32 v15, v15
	v_add_f32_e32 v232, v232, v14
	v_add_f32_e32 v233, v233, v15
	v_cvt_pk_bf16_f32 v8, v8, v9
	v_cvt_pk_bf16_f32 v9, v10, v11
	v_cvt_pk_bf16_f32 v10, v12, v13
	v_cvt_pk_bf16_f32 v11, v14, v15
	s_waitcnt lgkmcnt(11)
	s_nop 0
	v_mfma_f32_32x32x16_bf16 v[48:63], v[212:215], v[8:11], v[48:63]
	s_waitcnt lgkmcnt(10)
	v_mfma_f32_32x32x16_bf16 v[32:47], v[216:219], v[8:11], v[32:47]
	ds_read_b128 v[204:207], v249 offset:9280
	ds_read_b128 v[208:211], v249 offset:13888
	ds_read_b128 v[212:215], v249 offset:9312
	ds_read_b128 v[216:219], v249 offset:13920
	v_add_f32_e32 v16, v16, v194
	v_cndmask_b32_e64 v16, v203, v16, s[80:81]
	ds_read_b32 v194, v182 offset:124
	s_waitcnt lgkmcnt(14)
	v_add_f32_e32 v17, v17, v195
	v_cndmask_b32_e64 v17, v203, v17, s[82:83]
	ds_read_b32 v195, v183 offset:124
	s_waitcnt lgkmcnt(14)
	v_add_f32_e32 v18, v18, v196
	v_cndmask_b32_e64 v18, v203, v18, s[84:85]
	ds_read_b32 v196, v184 offset:124
	s_waitcnt lgkmcnt(14)
	v_add_f32_e32 v19, v19, v197
	v_cndmask_b32_e64 v19, v203, v19, s[86:87]
	ds_read_b32 v197, v185 offset:124
	s_waitcnt lgkmcnt(14)
	v_add_f32_e32 v20, v20, v198
	v_cndmask_b32_e64 v20, v203, v20, s[88:89]
	ds_read_b32 v198, v186 offset:124
	s_waitcnt lgkmcnt(14)
	v_add_f32_e32 v21, v21, v199
	v_cndmask_b32_e64 v21, v203, v21, s[90:91]
	s_waitcnt lgkmcnt(13)
	v_add_f32_e32 v22, v22, v189
	v_cndmask_b32_e64 v22, v203, v22, s[92:93]
	s_waitcnt lgkmcnt(12)
	v_add_f32_e32 v23, v23, v190
	v_cndmask_b32_e64 v23, v203, v23, s[94:95]
	v_exp_f32_e32 v16, v16
	v_exp_f32_e32 v17, v17
	v_add_f32_e32 v232, v232, v16
	v_add_f32_e32 v233, v233, v17
	v_exp_f32_e32 v18, v18
	v_exp_f32_e32 v19, v19
	v_add_f32_e32 v232, v232, v18
	v_add_f32_e32 v233, v233, v19
	v_exp_f32_e32 v20, v20
	v_exp_f32_e32 v21, v21
	v_add_f32_e32 v232, v232, v20
	v_add_f32_e32 v233, v233, v21
	v_exp_f32_e32 v22, v22
	v_exp_f32_e32 v23, v23
	v_add_f32_e32 v232, v232, v22
	v_add_f32_e32 v233, v233, v23
	v_cvt_pk_bf16_f32 v16, v16, v17
	v_cvt_pk_bf16_f32 v17, v18, v19
	v_cvt_pk_bf16_f32 v18, v20, v21
	v_cvt_pk_bf16_f32 v19, v22, v23
	s_waitcnt lgkmcnt(8)
	s_nop 0
	v_mfma_f32_32x32x16_bf16 v[48:63], v[204:207], v[16:19], v[48:63]
	s_waitcnt lgkmcnt(7)
	v_mfma_f32_32x32x16_bf16 v[32:47], v[208:211], v[16:19], v[32:47]
	v_add_f32_e32 v24, v24, v191
	v_cndmask_b32_e64 v24, v203, v24, s[96:97]
	v_add_f32_e32 v25, v25, v192
	v_cndmask_b32_e64 v25, v203, v25, s[40:41]
	v_add_f32_e32 v26, v26, v193
	v_cndmask_b32_e64 v26, v203, v26, s[38:39]
	s_waitcnt lgkmcnt(4)
	v_add_f32_e32 v27, v27, v194
	v_cndmask_b32_e64 v27, v203, v27, s[44:45]
	s_waitcnt lgkmcnt(3)
	v_add_f32_e32 v28, v28, v195
	v_cndmask_b32_e64 v28, v203, v28, s[4:5]
	s_waitcnt lgkmcnt(2)
	v_add_f32_e32 v29, v29, v196
	v_cndmask_b32_e64 v29, v203, v29, s[42:43]
	s_waitcnt lgkmcnt(1)
	v_add_f32_e32 v30, v30, v197
	v_cndmask_b32_e64 v30, v203, v30, s[50:51]
	s_waitcnt lgkmcnt(0)
	v_add_f32_e32 v31, v31, v198
	v_cndmask_b32_e64 v31, v203, v31, s[6:7]
	v_exp_f32_e32 v24, v24
	v_exp_f32_e32 v25, v25
	v_add_f32_e32 v232, v232, v24
	v_add_f32_e32 v233, v233, v25
	v_exp_f32_e32 v26, v26
	v_exp_f32_e32 v27, v27
	v_add_f32_e32 v232, v232, v26
	v_add_f32_e32 v233, v233, v27
	v_exp_f32_e32 v28, v28
	v_exp_f32_e32 v29, v29
	v_add_f32_e32 v232, v232, v28
	v_add_f32_e32 v233, v233, v29
	v_exp_f32_e32 v30, v30
	v_exp_f32_e32 v31, v31
	v_add_f32_e32 v232, v232, v30
	v_add_f32_e32 v233, v233, v31
	v_cvt_pk_bf16_f32 v24, v24, v25
	v_cvt_pk_bf16_f32 v25, v26, v27
	v_cvt_pk_bf16_f32 v26, v28, v29
	v_cvt_pk_bf16_f32 v27, v30, v31
	s_nop 1
	v_mfma_f32_32x32x16_bf16 v[48:63], v[212:215], v[24:27], v[48:63]
	v_mfma_f32_32x32x16_bf16 v[32:47], v[216:219], v[24:27], v[32:47]
	v_add_f32_e32 v232, v232, v233
	v_cmp_lt_f32_e32 vcc, s33, v232
	s_cbranch_vccz .Lna_nr1
	s_nop 15
	v_and_b32_e32 v243, 64, v237
	v_xor_b32_e32 v242, 32, v237
	v_add_u32_e32 v243, 64, v243
	v_cmp_lt_i32_e32 vcc, v242, v243
	s_nop 1
	v_cndmask_b32_e32 v242, v237, v242, vcc
	v_lshlrev_b32_e32 v242, 2, v242
	ds_bpermute_b32 v242, v242, v232
	s_waitcnt lgkmcnt(0)
	v_add_f32_e32 v242, v242, v232
	v_frexp_exp_i32_f32_e32 v242, v242
	v_max_i32_e32 v242, 1, v242
	v_add_u32_e32 v242, -1, v242
	v_cvt_f32_u32_e32 v242, v242
	v_exp_f32_e64 v243, -v242
	v_add_f32_e32 v188, v188, v242
	v_xor_b32_e32 v64, 0x80000000, v188
	v_mul_f32_e32 v187, v187, v243
	v_mul_f32_e32 v232, v232, v243
	v_mul_f32_e32 v32, v32, v243
	v_mul_f32_e32 v33, v33, v243
	v_mul_f32_e32 v34, v34, v243
	v_mul_f32_e32 v35, v35, v243
	v_mul_f32_e32 v36, v36, v243
	v_mul_f32_e32 v37, v37, v243
	v_mul_f32_e32 v38, v38, v243
	v_mul_f32_e32 v39, v39, v243
	v_mul_f32_e32 v40, v40, v243
	v_mul_f32_e32 v41, v41, v243
	v_mul_f32_e32 v42, v42, v243
	v_mul_f32_e32 v43, v43, v243
	v_mul_f32_e32 v44, v44, v243
	v_mul_f32_e32 v45, v45, v243
	v_mul_f32_e32 v46, v46, v243
	v_mul_f32_e32 v47, v47, v243
	v_mul_f32_e32 v48, v48, v243
	v_mul_f32_e32 v49, v49, v243
	v_mul_f32_e32 v50, v50, v243
	v_mul_f32_e32 v51, v51, v243
	v_mul_f32_e32 v52, v52, v243
	v_mul_f32_e32 v53, v53, v243
	v_mul_f32_e32 v54, v54, v243
	v_mul_f32_e32 v55, v55, v243
	v_mul_f32_e32 v56, v56, v243
	v_mul_f32_e32 v57, v57, v243
	v_mul_f32_e32 v58, v58, v243
	v_mul_f32_e32 v59, v59, v243
	v_mul_f32_e32 v60, v60, v243
	v_mul_f32_e32 v61, v61, v243
	v_mul_f32_e32 v62, v62, v243
	v_mul_f32_e32 v63, v63, v243
	v_mov_b32_e32 v65, v64
	v_mov_b32_e32 v66, v64
	v_mov_b32_e32 v67, v64
	v_mov_b32_e32 v68, v64
	v_mov_b32_e32 v69, v64
	v_mov_b32_e32 v70, v64
	v_mov_b32_e32 v71, v64
	v_mov_b32_e32 v72, v64
	v_mov_b32_e32 v73, v64
	v_mov_b32_e32 v74, v64
	v_mov_b32_e32 v75, v64
	v_mov_b32_e32 v76, v64
	v_mov_b32_e32 v77, v64
	v_mov_b32_e32 v78, v64
	v_mov_b32_e32 v79, v64
.Lna_nr1:
	v_add_f32_e32 v187, v187, v232
	v_add_u32_e32 v242, 0x0, v147
	s_waitcnt vmcnt(15)
	ds_write_b128 v242, v[120:123]
	s_waitcnt vmcnt(13)
	ds_write_b128 v242, v[112:115] offset:9216
	ds_write_b128 v242, v[124:127] offset:18432
	s_waitcnt vmcnt(12)
	ds_write_b128 v242, v[116:119] offset:27648
	s_waitcnt vmcnt(11)
	ds_write_b128 v242, v[128:131] offset:36864
	s_waitcnt vmcnt(9)
	ds_write_b128 v242, v[132:135] offset:46080
	ds_write_b128 v242, v[136:139] offset:55296
	s_waitcnt vmcnt(8)
	ds_write_b128 v242, v[140:143] offset:64512
	s_waitcnt lgkmcnt(0)
	s_barrier
.Lna_it2:
	s_add_i32 s17, s37, 0x0
	v_add3_u32 v248, s17, v146, v149
	v_add3_u32 v249, s17, v154, v146
	ds_read_b128 v[204:207], v248
	ds_read_b128 v[208:211], v248 offset:32
	ds_read_b128 v[212:215], v248 offset:64
	ds_read_b128 v[216:219], v248 offset:96
	v_lshl_add_u64 v[2:3], v[152:153], 0, v[200:201]
	v_add_co_u32_e32 v4, vcc, 0x12d00000, v2
	v_lshl_add_u64 v[0:1], v[150:151], 0, v[200:201]
	s_nop 0
	v_addc_co_u32_e32 v5, vcc, 0, v3, vcc
	v_add_co_u32_e32 v6, vcc, 0x12e00000, v2
	global_load_dwordx4 v[120:123], v[0:1], off offset:-256
	global_load_dwordx4 v[124:127], v[0:1], off offset:-128
	v_addc_co_u32_e32 v7, vcc, 0, v3, vcc
	global_load_dwordx4 v[112:115], v[4:5], off offset:128
	global_load_dwordx4 v[116:119], v[6:7], off offset:128
	v_add_co_u32_e32 v4, vcc, 0x12f00000, v2
	global_load_dwordx4 v[128:131], v[0:1], off
	global_load_dwordx4 v[136:139], v[0:1], off offset:128
	v_addc_co_u32_e32 v5, vcc, 0, v3, vcc
	v_add_co_u32_e32 v0, vcc, 0x13000000, v2
	s_nop 1
	v_addc_co_u32_e32 v1, vcc, 0, v3, vcc
	global_load_dwordx4 v[132:135], v[4:5], off offset:128
	global_load_dwordx4 v[140:143], v[0:1], off offset:128
	v_lshl_add_u64 v[152:153], v[152:153], 0, s[26:27]
	v_lshl_add_u64 v[150:151], v[150:151], 0, s[28:29]
	v_mov_b32_e32 v203, 0xf149f2ca
	ds_read_b32 v189, v155 offset:248
	ds_read_b32 v190, v156 offset:248
	ds_read_b32 v191, v157 offset:248
	ds_read_b32 v192, v158 offset:248
	ds_read_b32 v193, v159 offset:248
	ds_read_b32 v194, v160 offset:248
	ds_read_b32 v195, v161 offset:248
	ds_read_b32 v196, v162 offset:248
	ds_read_b32 v197, v163 offset:248
	ds_read_b32 v198, v164 offset:248
	ds_read_b32 v199, v165 offset:248
	s_waitcnt lgkmcnt(14)
	v_mfma_f32_32x32x16_bf16 v[0:15], v[204:207], v[96:99], v[64:79]
	s_waitcnt lgkmcnt(13)
	v_mfma_f32_32x32x16_bf16 v[0:15], v[208:211], v[100:103], v[0:15]
	s_waitcnt lgkmcnt(12)
	v_mfma_f32_32x32x16_bf16 v[0:15], v[212:215], v[104:107], v[0:15]
	s_waitcnt lgkmcnt(11)
	v_mfma_f32_32x32x16_bf16 v[0:15], v[216:219], v[108:111], v[0:15]
	ds_read_b128 v[204:207], v248 offset:4608
	ds_read_b128 v[208:211], v248 offset:4640
	ds_read_b128 v[212:215], v248 offset:4672
	ds_read_b128 v[216:219], v248 offset:4704
	s_waitcnt lgkmcnt(3)
	v_mfma_f32_32x32x16_bf16 v[16:31], v[204:207], v[96:99], v[64:79]
	s_nop 5
	v_add_f32_e32 v0, v0, v189
	v_cndmask_b32_e64 v0, v203, v0, s[2:3]
	ds_read_b32 v189, v166 offset:248
	v_add_f32_e32 v1, v1, v190
	v_cndmask_b32_e64 v1, v203, v1, s[48:49]
	ds_read_b32 v190, v167 offset:248
	s_waitcnt lgkmcnt(4)
	v_mfma_f32_32x32x16_bf16 v[16:31], v[208:211], v[100:103], v[16:31]
	v_add_f32_e32 v2, v2, v191
	v_cndmask_b32_e64 v2, v203, v2, s[52:53]
	ds_read_b32 v191, v168 offset:248
	v_add_f32_e32 v3, v3, v192
	v_cndmask_b32_e64 v3, v203, v3, s[54:55]
	ds_read_b32 v192, v169 offset:248
	s_waitcnt lgkmcnt(5)
	v_mfma_f32_32x32x16_bf16 v[16:31], v[212:215], v[104:107], v[16:31]
	v_add_f32_e32 v4, v4, v193
	v_cndmask_b32_e64 v4, v203, v4, s[56:57]
	ds_read_b32 v193, v170 offset:248
	v_add_f32_e32 v5, v5, v194
	v_cndmask_b32_e64 v5, v203, v5, s[58:59]
	ds_read_b32 v194, v171 offset:248
	s_waitcnt lgkmcnt(6)
	v_mfma_f32_32x32x16_bf16 v[16:31], v[216:219], v[108:111], v[16:31]
	ds_read_b128 v[204:207], v249 offset:9216
	ds_read_b128 v[208:211], v249 offset:13824
	ds_read_b128 v[212:215], v249 offset:9248
	ds_read_b128 v[216:219], v249 offset:13856
	v_add_f32_e32 v6, v6, v195
	v_cndmask_b32_e64 v6, v203, v6, s[60:61]
	ds_read_b32 v195, v172 offset:248
	v_add_f32_e32 v7, v7, v196
	v_cndmask_b32_e64 v7, v203, v7, s[62:63]
	ds_read_b32 v196, v173 offset:248
	v_exp_f32_e32 v0, v0
	v_exp_f32_e32 v1, v1
	v_exp_f32_e32 v2, v2
	v_exp_f32_e32 v3, v3
	v_add_f32_e32 v232, v0, v2
	v_add_f32_e32 v233, v1, v3
	v_exp_f32_e32 v4, v4
	v_exp_f32_e32 v5, v5
	v_add_f32_e32 v232, v232, v4
	v_add_f32_e32 v233, v233, v5
	v_exp_f32_e32 v6, v6
	v_exp_f32_e32 v7, v7
	v_add_f32_e32 v232, v232, v6
	v_add_f32_e32 v233, v233, v7
	v_cvt_pk_bf16_f32 v0, v0, v1
	v_cvt_pk_bf16_f32 v1, v2, v3
	v_cvt_pk_bf16_f32 v2, v4, v5
	v_cvt_pk_bf16_f32 v3, v6, v7
	s_waitcnt lgkmcnt(5)
	s_nop 0
	v_mfma_f32_32x32x16_bf16 v[48:63], v[204:207], v[0:3], v[48:63]
	s_waitcnt lgkmcnt(4)
	v_mfma_f32_32x32x16_bf16 v[32:47], v[208:211], v[0:3], v[32:47]
	v_add_f32_e32 v8, v8, v197
	v_cndmask_b32_e64 v8, v203, v8, s[64:65]
	ds_read_b32 v197, v174 offset:248
	v_add_f32_e32 v9, v9, v198
	v_cndmask_b32_e64 v9, v203, v9, s[66:67]
	ds_read_b32 v198, v175 offset:248
	v_add_f32_e32 v10, v10, v199
	v_cndmask_b32_e64 v10, v203, v10, s[68:69]
	ds_read_b32 v199, v176 offset:248
	v_add_f32_e32 v11, v11, v189
	v_cndmask_b32_e64 v11, v203, v11, s[70:71]
	ds_read_b32 v189, v177 offset:248
	v_add_f32_e32 v12, v12, v190
	v_cndmask_b32_e64 v12, v203, v12, s[72:73]
	ds_read_b32 v190, v178 offset:248
	v_add_f32_e32 v13, v13, v191
	v_cndmask_b32_e64 v13, v203, v13, s[74:75]
	ds_read_b32 v191, v179 offset:248
	v_add_f32_e32 v14, v14, v192
	v_cndmask_b32_e64 v14, v203, v14, s[76:77]
	ds_read_b32 v192, v180 offset:248
	v_add_f32_e32 v15, v15, v193
	v_cndmask_b32_e64 v15, v203, v15, s[78:79]
	ds_read_b32 v193, v181 offset:248
	v_exp_f32_e32 v8, v8
	v_exp_f32_e32 v9, v9
	v_add_f32_e32 v232, v232, v8
	v_add_f32_e32 v233, v233, v9
	v_exp_f32_e32 v10, v10
	v_exp_f32_e32 v11, v11
	v_add_f32_e32 v232, v232, v10
	v_add_f32_e32 v233, v233, v11
	v_exp_f32_e32 v12, v12
	v_exp_f32_e32 v13, v13
	v_add_f32_e32 v232, v232, v12
	v_add_f32_e32 v233, v233, v13
	v_exp_f32_e32 v14, v14
	v_exp_f32_e32 v15, v15
	v_add_f32_e32 v232, v232, v14
	v_add_f32_e32 v233, v233, v15
	v_cvt_pk_bf16_f32 v8, v8, v9
	v_cvt_pk_bf16_f32 v9, v10, v11
	v_cvt_pk_bf16_f32 v10, v12, v13
	v_cvt_pk_bf16_f32 v11, v14, v15
	s_waitcnt lgkmcnt(11)
	s_nop 0
	v_mfma_f32_32x32x16_bf16 v[48:63], v[212:215], v[8:11], v[48:63]
	s_waitcnt lgkmcnt(10)
	v_mfma_f32_32x32x16_bf16 v[32:47], v[216:219], v[8:11], v[32:47]
	ds_read_b128 v[204:207], v249 offset:9280
	ds_read_b128 v[208:211], v249 offset:13888
	ds_read_b128 v[212:215], v249 offset:9312
	ds_read_b128 v[216:219], v249 offset:13920
	v_add_f32_e32 v16, v16, v194
	v_cndmask_b32_e64 v16, v203, v16, s[80:81]
	ds_read_b32 v194, v182 offset:248
	s_waitcnt lgkmcnt(14)
	v_add_f32_e32 v17, v17, v195
	v_cndmask_b32_e64 v17, v203, v17, s[82:83]
	ds_read_b32 v195, v183 offset:248
	s_waitcnt lgkmcnt(14)
	v_add_f32_e32 v18, v18, v196
	v_cndmask_b32_e64 v18, v203, v18, s[84:85]
	ds_read_b32 v196, v184 offset:248
	s_waitcnt lgkmcnt(14)
	v_add_f32_e32 v19, v19, v197
	v_cndmask_b32_e64 v19, v203, v19, s[86:87]
	ds_read_b32 v197, v185 offset:248
	s_waitcnt lgkmcnt(14)
	v_add_f32_e32 v20, v20, v198
	v_cndmask_b32_e64 v20, v203, v20, s[88:89]
	ds_read_b32 v198, v186 offset:248
	s_waitcnt lgkmcnt(14)
	v_add_f32_e32 v21, v21, v199
	v_cndmask_b32_e64 v21, v203, v21, s[90:91]
	s_waitcnt lgkmcnt(13)
	v_add_f32_e32 v22, v22, v189
	v_cndmask_b32_e64 v22, v203, v22, s[92:93]
	s_waitcnt lgkmcnt(12)
	v_add_f32_e32 v23, v23, v190
	v_cndmask_b32_e64 v23, v203, v23, s[94:95]
	v_exp_f32_e32 v16, v16
	v_exp_f32_e32 v17, v17
	v_add_f32_e32 v232, v232, v16
	v_add_f32_e32 v233, v233, v17
	v_exp_f32_e32 v18, v18
	v_exp_f32_e32 v19, v19
	v_add_f32_e32 v232, v232, v18
	v_add_f32_e32 v233, v233, v19
	v_exp_f32_e32 v20, v20
	v_exp_f32_e32 v21, v21
	v_add_f32_e32 v232, v232, v20
	v_add_f32_e32 v233, v233, v21
	v_exp_f32_e32 v22, v22
	v_exp_f32_e32 v23, v23
	v_add_f32_e32 v232, v232, v22
	v_add_f32_e32 v233, v233, v23
	v_cvt_pk_bf16_f32 v16, v16, v17
	v_cvt_pk_bf16_f32 v17, v18, v19
	v_cvt_pk_bf16_f32 v18, v20, v21
	v_cvt_pk_bf16_f32 v19, v22, v23
	s_waitcnt lgkmcnt(8)
	s_nop 0
	v_mfma_f32_32x32x16_bf16 v[48:63], v[204:207], v[16:19], v[48:63]
	s_waitcnt lgkmcnt(7)
	v_mfma_f32_32x32x16_bf16 v[32:47], v[208:211], v[16:19], v[32:47]
	v_add_f32_e32 v24, v24, v191
	v_cndmask_b32_e64 v24, v203, v24, s[96:97]
	v_add_f32_e32 v25, v25, v192
	v_cndmask_b32_e64 v25, v203, v25, s[40:41]
	v_add_f32_e32 v26, v26, v193
	v_cndmask_b32_e64 v26, v203, v26, s[38:39]
	s_waitcnt lgkmcnt(4)
	v_add_f32_e32 v27, v27, v194
	v_cndmask_b32_e64 v27, v203, v27, s[44:45]
	s_waitcnt lgkmcnt(3)
	v_add_f32_e32 v28, v28, v195
	v_cndmask_b32_e64 v28, v203, v28, s[4:5]
	s_waitcnt lgkmcnt(2)
	v_add_f32_e32 v29, v29, v196
	v_cndmask_b32_e64 v29, v203, v29, s[42:43]
	s_waitcnt lgkmcnt(1)
	v_add_f32_e32 v30, v30, v197
	v_cndmask_b32_e64 v30, v203, v30, s[50:51]
	s_waitcnt lgkmcnt(0)
	v_add_f32_e32 v31, v31, v198
	v_cndmask_b32_e64 v31, v203, v31, s[6:7]
	v_exp_f32_e32 v24, v24
	v_exp_f32_e32 v25, v25
	v_add_f32_e32 v232, v232, v24
	v_add_f32_e32 v233, v233, v25
	v_exp_f32_e32 v26, v26
	v_exp_f32_e32 v27, v27
	v_add_f32_e32 v232, v232, v26
	v_add_f32_e32 v233, v233, v27
	v_exp_f32_e32 v28, v28
	v_exp_f32_e32 v29, v29
	v_add_f32_e32 v232, v232, v28
	v_add_f32_e32 v233, v233, v29
	v_exp_f32_e32 v30, v30
	v_exp_f32_e32 v31, v31
	v_add_f32_e32 v232, v232, v30
	v_add_f32_e32 v233, v233, v31
	v_cvt_pk_bf16_f32 v24, v24, v25
	v_cvt_pk_bf16_f32 v25, v26, v27
	v_cvt_pk_bf16_f32 v26, v28, v29
	v_cvt_pk_bf16_f32 v27, v30, v31
	s_nop 1
	v_mfma_f32_32x32x16_bf16 v[48:63], v[212:215], v[24:27], v[48:63]
	v_mfma_f32_32x32x16_bf16 v[32:47], v[216:219], v[24:27], v[32:47]
	v_add_f32_e32 v232, v232, v233
	v_cmp_lt_f32_e32 vcc, s33, v232
	s_cbranch_vccz .Lna_nr2
	s_nop 15
	v_and_b32_e32 v243, 64, v237
	v_xor_b32_e32 v242, 32, v237
	v_add_u32_e32 v243, 64, v243
	v_cmp_lt_i32_e32 vcc, v242, v243
	s_nop 1
	v_cndmask_b32_e32 v242, v237, v242, vcc
	v_lshlrev_b32_e32 v242, 2, v242
	ds_bpermute_b32 v242, v242, v232
	s_waitcnt lgkmcnt(0)
	v_add_f32_e32 v242, v242, v232
	v_frexp_exp_i32_f32_e32 v242, v242
	v_max_i32_e32 v242, 1, v242
	v_add_u32_e32 v242, -1, v242
	v_cvt_f32_u32_e32 v242, v242
	v_exp_f32_e64 v243, -v242
	v_add_f32_e32 v188, v188, v242
	v_xor_b32_e32 v64, 0x80000000, v188
	v_mul_f32_e32 v187, v187, v243
	v_mul_f32_e32 v232, v232, v243
	v_mul_f32_e32 v32, v32, v243
	v_mul_f32_e32 v33, v33, v243
	v_mul_f32_e32 v34, v34, v243
	v_mul_f32_e32 v35, v35, v243
	v_mul_f32_e32 v36, v36, v243
	v_mul_f32_e32 v37, v37, v243
	v_mul_f32_e32 v38, v38, v243
	v_mul_f32_e32 v39, v39, v243
	v_mul_f32_e32 v40, v40, v243
	v_mul_f32_e32 v41, v41, v243
	v_mul_f32_e32 v42, v42, v243
	v_mul_f32_e32 v43, v43, v243
	v_mul_f32_e32 v44, v44, v243
	v_mul_f32_e32 v45, v45, v243
	v_mul_f32_e32 v46, v46, v243
	v_mul_f32_e32 v47, v47, v243
	v_mul_f32_e32 v48, v48, v243
	v_mul_f32_e32 v49, v49, v243
	v_mul_f32_e32 v50, v50, v243
	v_mul_f32_e32 v51, v51, v243
	v_mul_f32_e32 v52, v52, v243
	v_mul_f32_e32 v53, v53, v243
	v_mul_f32_e32 v54, v54, v243
	v_mul_f32_e32 v55, v55, v243
	v_mul_f32_e32 v56, v56, v243
	v_mul_f32_e32 v57, v57, v243
	v_mul_f32_e32 v58, v58, v243
	v_mul_f32_e32 v59, v59, v243
	v_mul_f32_e32 v60, v60, v243
	v_mul_f32_e32 v61, v61, v243
	v_mul_f32_e32 v62, v62, v243
	v_mul_f32_e32 v63, v63, v243
	v_mov_b32_e32 v65, v64
	v_mov_b32_e32 v66, v64
	v_mov_b32_e32 v67, v64
	v_mov_b32_e32 v68, v64
	v_mov_b32_e32 v69, v64
	v_mov_b32_e32 v70, v64
	v_mov_b32_e32 v71, v64
	v_mov_b32_e32 v72, v64
	v_mov_b32_e32 v73, v64
	v_mov_b32_e32 v74, v64
	v_mov_b32_e32 v75, v64
	v_mov_b32_e32 v76, v64
	v_mov_b32_e32 v77, v64
	v_mov_b32_e32 v78, v64
	v_mov_b32_e32 v79, v64
.Lna_nr2:
	v_add_f32_e32 v187, v187, v232
	v_add_u32_e32 v242, 0x12000, v147
	s_waitcnt vmcnt(15)
	ds_write_b128 v242, v[80:83]
	s_waitcnt vmcnt(13)
	ds_write_b128 v242, v[88:91] offset:9216
	ds_write_b128 v242, v[84:87] offset:18432
	s_waitcnt vmcnt(12)
	ds_write_b128 v242, v[92:95] offset:27648
	s_waitcnt vmcnt(11)
	ds_write_b128 v242, v[220:223] offset:36864
	s_waitcnt vmcnt(9)
	ds_write_b128 v242, v[228:231] offset:46080
	ds_write_b128 v242, v[224:227] offset:55296
	s_waitcnt vmcnt(8)
	ds_write_b128 v242, v[244:247] offset:64512
	s_waitcnt lgkmcnt(0)
	s_barrier
.Lna_it3:
	s_add_i32 s17, s37, 0x12000
	v_add3_u32 v248, s17, v146, v149
	v_add3_u32 v249, s17, v154, v146
	ds_read_b128 v[204:207], v248
	ds_read_b128 v[208:211], v248 offset:32
	ds_read_b128 v[212:215], v248 offset:64
	ds_read_b128 v[216:219], v248 offset:96
	v_lshl_add_u64 v[2:3], v[152:153], 0, v[200:201]
	v_add_co_u32_e32 v4, vcc, 0x12d00000, v2
	v_lshl_add_u64 v[0:1], v[150:151], 0, v[200:201]
	s_nop 0
	v_addc_co_u32_e32 v5, vcc, 0, v3, vcc
	v_add_co_u32_e32 v6, vcc, 0x12e00000, v2
	global_load_dwordx4 v[80:83], v[0:1], off offset:-256
	global_load_dwordx4 v[84:87], v[0:1], off offset:-128
	v_addc_co_u32_e32 v7, vcc, 0, v3, vcc
	global_load_dwordx4 v[88:91], v[4:5], off offset:128
	global_load_dwordx4 v[92:95], v[6:7], off offset:128
	v_add_co_u32_e32 v4, vcc, 0x12f00000, v2
	global_load_dwordx4 v[220:223], v[0:1], off
	global_load_dwordx4 v[224:227], v[0:1], off offset:128
	v_addc_co_u32_e32 v5, vcc, 0, v3, vcc
	v_add_co_u32_e32 v0, vcc, 0x13000000, v2
	s_nop 1
	v_addc_co_u32_e32 v1, vcc, 0, v3, vcc
	global_load_dwordx4 v[228:231], v[4:5], off offset:128
	global_load_dwordx4 v[244:247], v[0:1], off offset:128
	v_lshl_add_u64 v[152:153], v[152:153], 0, s[26:27]
	v_lshl_add_u64 v[150:151], v[150:151], 0, s[28:29]
	v_mov_b32_e32 v203, 0xf149f2ca
	ds_read_b32 v189, v155 offset:372
	ds_read_b32 v190, v156 offset:372
	ds_read_b32 v191, v157 offset:372
	ds_read_b32 v192, v158 offset:372
	ds_read_b32 v193, v159 offset:372
	ds_read_b32 v194, v160 offset:372
	ds_read_b32 v195, v161 offset:372
	ds_read_b32 v196, v162 offset:372
	ds_read_b32 v197, v163 offset:372
	ds_read_b32 v198, v164 offset:372
	ds_read_b32 v199, v165 offset:372
	s_waitcnt lgkmcnt(14)
	v_mfma_f32_32x32x16_bf16 v[0:15], v[204:207], v[96:99], v[64:79]
	s_waitcnt lgkmcnt(13)
	v_mfma_f32_32x32x16_bf16 v[0:15], v[208:211], v[100:103], v[0:15]
	s_waitcnt lgkmcnt(12)
	v_mfma_f32_32x32x16_bf16 v[0:15], v[212:215], v[104:107], v[0:15]
	s_waitcnt lgkmcnt(11)
	v_mfma_f32_32x32x16_bf16 v[0:15], v[216:219], v[108:111], v[0:15]
	ds_read_b128 v[204:207], v248 offset:4608
	ds_read_b128 v[208:211], v248 offset:4640
	ds_read_b128 v[212:215], v248 offset:4672
	ds_read_b128 v[216:219], v248 offset:4704
	s_waitcnt lgkmcnt(3)
	v_mfma_f32_32x32x16_bf16 v[16:31], v[204:207], v[96:99], v[64:79]
	s_nop 5
	v_add_f32_e32 v0, v0, v189
	v_cndmask_b32_e64 v0, v203, v0, s[2:3]
	ds_read_b32 v189, v166 offset:372
	v_add_f32_e32 v1, v1, v190
	v_cndmask_b32_e64 v1, v203, v1, s[48:49]
	ds_read_b32 v190, v167 offset:372
	s_waitcnt lgkmcnt(4)
	v_mfma_f32_32x32x16_bf16 v[16:31], v[208:211], v[100:103], v[16:31]
	v_add_f32_e32 v2, v2, v191
	v_cndmask_b32_e64 v2, v203, v2, s[52:53]
	ds_read_b32 v191, v168 offset:372
	v_add_f32_e32 v3, v3, v192
	v_cndmask_b32_e64 v3, v203, v3, s[54:55]
	ds_read_b32 v192, v169 offset:372
	s_waitcnt lgkmcnt(5)
	v_mfma_f32_32x32x16_bf16 v[16:31], v[212:215], v[104:107], v[16:31]
	v_add_f32_e32 v4, v4, v193
	v_cndmask_b32_e64 v4, v203, v4, s[56:57]
	ds_read_b32 v193, v170 offset:372
	v_add_f32_e32 v5, v5, v194
	v_cndmask_b32_e64 v5, v203, v5, s[58:59]
	ds_read_b32 v194, v171 offset:372
	s_waitcnt lgkmcnt(6)
	v_mfma_f32_32x32x16_bf16 v[16:31], v[216:219], v[108:111], v[16:31]
	ds_read_b128 v[204:207], v249 offset:9216
	ds_read_b128 v[208:211], v249 offset:13824
	ds_read_b128 v[212:215], v249 offset:9248
	ds_read_b128 v[216:219], v249 offset:13856
	v_add_f32_e32 v6, v6, v195
	v_cndmask_b32_e64 v6, v203, v6, s[60:61]
	ds_read_b32 v195, v172 offset:372
	v_add_f32_e32 v7, v7, v196
	v_cndmask_b32_e64 v7, v203, v7, s[62:63]
	ds_read_b32 v196, v173 offset:372
	v_exp_f32_e32 v0, v0
	v_exp_f32_e32 v1, v1
	v_exp_f32_e32 v2, v2
	v_exp_f32_e32 v3, v3
	v_add_f32_e32 v232, v0, v2
	v_add_f32_e32 v233, v1, v3
	v_exp_f32_e32 v4, v4
	v_exp_f32_e32 v5, v5
	v_add_f32_e32 v232, v232, v4
	v_add_f32_e32 v233, v233, v5
	v_exp_f32_e32 v6, v6
	v_exp_f32_e32 v7, v7
	v_add_f32_e32 v232, v232, v6
	v_add_f32_e32 v233, v233, v7
	v_cvt_pk_bf16_f32 v0, v0, v1
	v_cvt_pk_bf16_f32 v1, v2, v3
	v_cvt_pk_bf16_f32 v2, v4, v5
	v_cvt_pk_bf16_f32 v3, v6, v7
	s_waitcnt lgkmcnt(5)
	s_nop 0
	v_mfma_f32_32x32x16_bf16 v[48:63], v[204:207], v[0:3], v[48:63]
	s_waitcnt lgkmcnt(4)
	v_mfma_f32_32x32x16_bf16 v[32:47], v[208:211], v[0:3], v[32:47]
	v_add_f32_e32 v8, v8, v197
	v_cndmask_b32_e64 v8, v203, v8, s[64:65]
	ds_read_b32 v197, v174 offset:372
	v_add_f32_e32 v9, v9, v198
	v_cndmask_b32_e64 v9, v203, v9, s[66:67]
	ds_read_b32 v198, v175 offset:372
	v_add_f32_e32 v10, v10, v199
	v_cndmask_b32_e64 v10, v203, v10, s[68:69]
	ds_read_b32 v199, v176 offset:372
	v_add_f32_e32 v11, v11, v189
	v_cndmask_b32_e64 v11, v203, v11, s[70:71]
	ds_read_b32 v189, v177 offset:372
	v_add_f32_e32 v12, v12, v190
	v_cndmask_b32_e64 v12, v203, v12, s[72:73]
	ds_read_b32 v190, v178 offset:372
	v_add_f32_e32 v13, v13, v191
	v_cndmask_b32_e64 v13, v203, v13, s[74:75]
	ds_read_b32 v191, v179 offset:372
	v_add_f32_e32 v14, v14, v192
	v_cndmask_b32_e64 v14, v203, v14, s[76:77]
	ds_read_b32 v192, v180 offset:372
	v_add_f32_e32 v15, v15, v193
	v_cndmask_b32_e64 v15, v203, v15, s[78:79]
	ds_read_b32 v193, v181 offset:372
	v_exp_f32_e32 v8, v8
	v_exp_f32_e32 v9, v9
	v_add_f32_e32 v232, v232, v8
	v_add_f32_e32 v233, v233, v9
	v_exp_f32_e32 v10, v10
	v_exp_f32_e32 v11, v11
	v_add_f32_e32 v232, v232, v10
	v_add_f32_e32 v233, v233, v11
	v_exp_f32_e32 v12, v12
	v_exp_f32_e32 v13, v13
	v_add_f32_e32 v232, v232, v12
	v_add_f32_e32 v233, v233, v13
	v_exp_f32_e32 v14, v14
	v_exp_f32_e32 v15, v15
	v_add_f32_e32 v232, v232, v14
	v_add_f32_e32 v233, v233, v15
	v_cvt_pk_bf16_f32 v8, v8, v9
	v_cvt_pk_bf16_f32 v9, v10, v11
	v_cvt_pk_bf16_f32 v10, v12, v13
	v_cvt_pk_bf16_f32 v11, v14, v15
	s_waitcnt lgkmcnt(11)
	s_nop 0
	v_mfma_f32_32x32x16_bf16 v[48:63], v[212:215], v[8:11], v[48:63]
	s_waitcnt lgkmcnt(10)
	v_mfma_f32_32x32x16_bf16 v[32:47], v[216:219], v[8:11], v[32:47]
	ds_read_b128 v[204:207], v249 offset:9280
	ds_read_b128 v[208:211], v249 offset:13888
	ds_read_b128 v[212:215], v249 offset:9312
	ds_read_b128 v[216:219], v249 offset:13920
	v_add_f32_e32 v16, v16, v194
	v_cndmask_b32_e64 v16, v203, v16, s[80:81]
	ds_read_b32 v194, v182 offset:372
	s_waitcnt lgkmcnt(14)
	v_add_f32_e32 v17, v17, v195
	v_cndmask_b32_e64 v17, v203, v17, s[82:83]
	ds_read_b32 v195, v183 offset:372
	s_waitcnt lgkmcnt(14)
	v_add_f32_e32 v18, v18, v196
	v_cndmask_b32_e64 v18, v203, v18, s[84:85]
	ds_read_b32 v196, v184 offset:372
	s_waitcnt lgkmcnt(14)
	v_add_f32_e32 v19, v19, v197
	v_cndmask_b32_e64 v19, v203, v19, s[86:87]
	ds_read_b32 v197, v185 offset:372
	s_waitcnt lgkmcnt(14)
	v_add_f32_e32 v20, v20, v198
	v_cndmask_b32_e64 v20, v203, v20, s[88:89]
	ds_read_b32 v198, v186 offset:372
	s_waitcnt lgkmcnt(14)
	v_add_f32_e32 v21, v21, v199
	v_cndmask_b32_e64 v21, v203, v21, s[90:91]
	s_waitcnt lgkmcnt(13)
	v_add_f32_e32 v22, v22, v189
	v_cndmask_b32_e64 v22, v203, v22, s[92:93]
	s_waitcnt lgkmcnt(12)
	v_add_f32_e32 v23, v23, v190
	v_cndmask_b32_e64 v23, v203, v23, s[94:95]
	v_exp_f32_e32 v16, v16
	v_exp_f32_e32 v17, v17
	v_add_f32_e32 v232, v232, v16
	v_add_f32_e32 v233, v233, v17
	v_exp_f32_e32 v18, v18
	v_exp_f32_e32 v19, v19
	v_add_f32_e32 v232, v232, v18
	v_add_f32_e32 v233, v233, v19
	v_exp_f32_e32 v20, v20
	v_exp_f32_e32 v21, v21
	v_add_f32_e32 v232, v232, v20
	v_add_f32_e32 v233, v233, v21
	v_exp_f32_e32 v22, v22
	v_exp_f32_e32 v23, v23
	v_add_f32_e32 v232, v232, v22
	v_add_f32_e32 v233, v233, v23
	v_cvt_pk_bf16_f32 v16, v16, v17
	v_cvt_pk_bf16_f32 v17, v18, v19
	v_cvt_pk_bf16_f32 v18, v20, v21
	v_cvt_pk_bf16_f32 v19, v22, v23
	s_waitcnt lgkmcnt(8)
	s_nop 0
	v_mfma_f32_32x32x16_bf16 v[48:63], v[204:207], v[16:19], v[48:63]
	s_waitcnt lgkmcnt(7)
	v_mfma_f32_32x32x16_bf16 v[32:47], v[208:211], v[16:19], v[32:47]
	v_add_f32_e32 v24, v24, v191
	v_cndmask_b32_e64 v24, v203, v24, s[96:97]
	v_add_f32_e32 v25, v25, v192
	v_cndmask_b32_e64 v25, v203, v25, s[40:41]
	v_add_f32_e32 v26, v26, v193
	v_cndmask_b32_e64 v26, v203, v26, s[38:39]
	s_waitcnt lgkmcnt(4)
	v_add_f32_e32 v27, v27, v194
	v_cndmask_b32_e64 v27, v203, v27, s[44:45]
	s_waitcnt lgkmcnt(3)
	v_add_f32_e32 v28, v28, v195
	v_cndmask_b32_e64 v28, v203, v28, s[4:5]
	s_waitcnt lgkmcnt(2)
	v_add_f32_e32 v29, v29, v196
	v_cndmask_b32_e64 v29, v203, v29, s[42:43]
	s_waitcnt lgkmcnt(1)
	v_add_f32_e32 v30, v30, v197
	v_cndmask_b32_e64 v30, v203, v30, s[50:51]
	s_waitcnt lgkmcnt(0)
	v_add_f32_e32 v31, v31, v198
	v_cndmask_b32_e64 v31, v203, v31, s[6:7]
	v_exp_f32_e32 v24, v24
	v_exp_f32_e32 v25, v25
	v_add_f32_e32 v232, v232, v24
	v_add_f32_e32 v233, v233, v25
	v_exp_f32_e32 v26, v26
	v_exp_f32_e32 v27, v27
	v_add_f32_e32 v232, v232, v26
	v_add_f32_e32 v233, v233, v27
	v_exp_f32_e32 v28, v28
	v_exp_f32_e32 v29, v29
	v_add_f32_e32 v232, v232, v28
	v_add_f32_e32 v233, v233, v29
	v_exp_f32_e32 v30, v30
	v_exp_f32_e32 v31, v31
	v_add_f32_e32 v232, v232, v30
	v_add_f32_e32 v233, v233, v31
	v_cvt_pk_bf16_f32 v24, v24, v25
	v_cvt_pk_bf16_f32 v25, v26, v27
	v_cvt_pk_bf16_f32 v26, v28, v29
	v_cvt_pk_bf16_f32 v27, v30, v31
	s_nop 1
	v_mfma_f32_32x32x16_bf16 v[48:63], v[212:215], v[24:27], v[48:63]
	v_mfma_f32_32x32x16_bf16 v[32:47], v[216:219], v[24:27], v[32:47]
	v_add_f32_e32 v232, v232, v233
	v_cmp_lt_f32_e32 vcc, s33, v232
	s_cbranch_vccz .Lna_nr3
	s_nop 15
	v_and_b32_e32 v243, 64, v237
	v_xor_b32_e32 v242, 32, v237
	v_add_u32_e32 v243, 64, v243
	v_cmp_lt_i32_e32 vcc, v242, v243
	s_nop 1
	v_cndmask_b32_e32 v242, v237, v242, vcc
	v_lshlrev_b32_e32 v242, 2, v242
	ds_bpermute_b32 v242, v242, v232
	s_waitcnt lgkmcnt(0)
	v_add_f32_e32 v242, v242, v232
	v_frexp_exp_i32_f32_e32 v242, v242
	v_max_i32_e32 v242, 1, v242
	v_add_u32_e32 v242, -1, v242
	v_cvt_f32_u32_e32 v242, v242
	v_exp_f32_e64 v243, -v242
	v_add_f32_e32 v188, v188, v242
	v_xor_b32_e32 v64, 0x80000000, v188
	v_mul_f32_e32 v187, v187, v243
	v_mul_f32_e32 v232, v232, v243
	v_mul_f32_e32 v32, v32, v243
	v_mul_f32_e32 v33, v33, v243
	v_mul_f32_e32 v34, v34, v243
	v_mul_f32_e32 v35, v35, v243
	v_mul_f32_e32 v36, v36, v243
	v_mul_f32_e32 v37, v37, v243
	v_mul_f32_e32 v38, v38, v243
	v_mul_f32_e32 v39, v39, v243
	v_mul_f32_e32 v40, v40, v243
	v_mul_f32_e32 v41, v41, v243
	v_mul_f32_e32 v42, v42, v243
	v_mul_f32_e32 v43, v43, v243
	v_mul_f32_e32 v44, v44, v243
	v_mul_f32_e32 v45, v45, v243
	v_mul_f32_e32 v46, v46, v243
	v_mul_f32_e32 v47, v47, v243
	v_mul_f32_e32 v48, v48, v243
	v_mul_f32_e32 v49, v49, v243
	v_mul_f32_e32 v50, v50, v243
	v_mul_f32_e32 v51, v51, v243
	v_mul_f32_e32 v52, v52, v243
	v_mul_f32_e32 v53, v53, v243
	v_mul_f32_e32 v54, v54, v243
	v_mul_f32_e32 v55, v55, v243
	v_mul_f32_e32 v56, v56, v243
	v_mul_f32_e32 v57, v57, v243
	v_mul_f32_e32 v58, v58, v243
	v_mul_f32_e32 v59, v59, v243
	v_mul_f32_e32 v60, v60, v243
	v_mul_f32_e32 v61, v61, v243
	v_mul_f32_e32 v62, v62, v243
	v_mul_f32_e32 v63, v63, v243
	v_mov_b32_e32 v65, v64
	v_mov_b32_e32 v66, v64
	v_mov_b32_e32 v67, v64
	v_mov_b32_e32 v68, v64
	v_mov_b32_e32 v69, v64
	v_mov_b32_e32 v70, v64
	v_mov_b32_e32 v71, v64
	v_mov_b32_e32 v72, v64
	v_mov_b32_e32 v73, v64
	v_mov_b32_e32 v74, v64
	v_mov_b32_e32 v75, v64
	v_mov_b32_e32 v76, v64
	v_mov_b32_e32 v77, v64
	v_mov_b32_e32 v78, v64
	v_mov_b32_e32 v79, v64

.Lna_it4:
	s_add_i32 s17, s37, 0x0
	v_add3_u32 v248, s17, v146, v149
	v_add3_u32 v249, s17, v154, v146
	ds_read_b128 v[204:207], v248
	ds_read_b128 v[208:211], v248 offset:32
	ds_read_b128 v[212:215], v248 offset:64
	ds_read_b128 v[216:219], v248 offset:96
	v_lshl_add_u64 v[2:3], v[152:153], 0, v[200:201]
	v_add_co_u32_e32 v4, vcc, 0x12d00000, v2
	v_lshl_add_u64 v[0:1], v[150:151], 0, v[200:201]
	s_nop 0
	v_addc_co_u32_e32 v5, vcc, 0, v3, vcc
	v_add_co_u32_e32 v6, vcc, 0x12e00000, v2
	global_load_dwordx4 v[120:123], v[0:1], off offset:-256
	global_load_dwordx4 v[124:127], v[0:1], off offset:-128
	v_addc_co_u32_e32 v7, vcc, 0, v3, vcc
	global_load_dwordx4 v[112:115], v[4:5], off offset:128
	global_load_dwordx4 v[116:119], v[6:7], off offset:128
	v_add_co_u32_e32 v4, vcc, 0x12f00000, v2
	global_load_dwordx4 v[128:131], v[0:1], off
	global_load_dwordx4 v[136:139], v[0:1], off offset:128
	v_addc_co_u32_e32 v5, vcc, 0, v3, vcc
	v_add_co_u32_e32 v0, vcc, 0x13000000, v2
	s_nop 1
	v_addc_co_u32_e32 v1, vcc, 0, v3, vcc
	global_load_dwordx4 v[132:135], v[4:5], off offset:128
	global_load_dwordx4 v[140:143], v[0:1], off offset:128
	v_lshl_add_u64 v[152:153], v[152:153], 0, s[26:27]
	v_lshl_add_u64 v[150:151], v[150:151], 0, s[28:29]
	v_mov_b32_e32 v203, 0xf149f2ca
	ds_read_b32 v189, v155 offset:496
	ds_read_b32 v190, v156 offset:496
	ds_read_b32 v191, v157 offset:496
	ds_read_b32 v192, v158 offset:496
	ds_read_b32 v193, v159 offset:496
	ds_read_b32 v194, v160 offset:496
	ds_read_b32 v195, v161 offset:496
	ds_read_b32 v196, v162 offset:496
	ds_read_b32 v197, v163 offset:496
	ds_read_b32 v198, v164 offset:496
	ds_read_b32 v199, v165 offset:496
	s_waitcnt lgkmcnt(14)
	v_mfma_f32_32x32x16_bf16 v[0:15], v[204:207], v[96:99], v[64:79]
	s_waitcnt lgkmcnt(13)
	v_mfma_f32_32x32x16_bf16 v[0:15], v[208:211], v[100:103], v[0:15]
	s_waitcnt lgkmcnt(12)
	v_mfma_f32_32x32x16_bf16 v[0:15], v[212:215], v[104:107], v[0:15]
	s_waitcnt lgkmcnt(11)
	v_mfma_f32_32x32x16_bf16 v[0:15], v[216:219], v[108:111], v[0:15]
	ds_read_b128 v[204:207], v248 offset:4608
	ds_read_b128 v[208:211], v248 offset:4640
	ds_read_b128 v[212:215], v248 offset:4672
	ds_read_b128 v[216:219], v248 offset:4704
	s_waitcnt lgkmcnt(3)
	v_mfma_f32_32x32x16_bf16 v[16:31], v[204:207], v[96:99], v[64:79]
	s_nop 5
	v_add_f32_e32 v0, v0, v189
	v_cndmask_b32_e64 v0, v203, v0, s[2:3]
	ds_read_b32 v189, v166 offset:496
	v_add_f32_e32 v1, v1, v190
	v_cndmask_b32_e64 v1, v203, v1, s[48:49]
	ds_read_b32 v190, v167 offset:496
	s_waitcnt lgkmcnt(4)
	v_mfma_f32_32x32x16_bf16 v[16:31], v[208:211], v[100:103], v[16:31]
	v_add_f32_e32 v2, v2, v191
	v_cndmask_b32_e64 v2, v203, v2, s[52:53]
	ds_read_b32 v191, v168 offset:496
	v_add_f32_e32 v3, v3, v192
	v_cndmask_b32_e64 v3, v203, v3, s[54:55]
	ds_read_b32 v192, v169 offset:496
	s_waitcnt lgkmcnt(5)
	v_mfma_f32_32x32x16_bf16 v[16:31], v[212:215], v[104:107], v[16:31]
	v_add_f32_e32 v4, v4, v193
	v_cndmask_b32_e64 v4, v203, v4, s[56:57]
	ds_read_b32 v193, v170 offset:496
	v_add_f32_e32 v5, v5, v194
	v_cndmask_b32_e64 v5, v203, v5, s[58:59]
	ds_read_b32 v194, v171 offset:496
	s_waitcnt lgkmcnt(6)
	v_mfma_f32_32x32x16_bf16 v[16:31], v[216:219], v[108:111], v[16:31]
	ds_read_b128 v[204:207], v249 offset:9216
	ds_read_b128 v[208:211], v249 offset:13824
	ds_read_b128 v[212:215], v249 offset:9248
	ds_read_b128 v[216:219], v249 offset:13856
	v_add_f32_e32 v6, v6, v195
	v_cndmask_b32_e64 v6, v203, v6, s[60:61]
	ds_read_b32 v195, v172 offset:496
	v_add_f32_e32 v7, v7, v196
	v_cndmask_b32_e64 v7, v203, v7, s[62:63]
	ds_read_b32 v196, v173 offset:496
	v_exp_f32_e32 v0, v0
	v_exp_f32_e32 v1, v1
	v_exp_f32_e32 v2, v2
	v_exp_f32_e32 v3, v3
	v_add_f32_e32 v232, v0, v2
	v_add_f32_e32 v233, v1, v3
	v_exp_f32_e32 v4, v4
	v_exp_f32_e32 v5, v5
	v_add_f32_e32 v232, v232, v4
	v_add_f32_e32 v233, v233, v5
	v_exp_f32_e32 v6, v6
	v_exp_f32_e32 v7, v7
	v_add_f32_e32 v232, v232, v6
	v_add_f32_e32 v233, v233, v7
	v_cvt_pk_bf16_f32 v0, v0, v1
	v_cvt_pk_bf16_f32 v1, v2, v3
	v_cvt_pk_bf16_f32 v2, v4, v5
	v_cvt_pk_bf16_f32 v3, v6, v7
	s_waitcnt lgkmcnt(5)
	s_nop 0
	v_mfma_f32_32x32x16_bf16 v[48:63], v[204:207], v[0:3], v[48:63]
	s_waitcnt lgkmcnt(4)
	v_mfma_f32_32x32x16_bf16 v[32:47], v[208:211], v[0:3], v[32:47]
	v_add_f32_e32 v8, v8, v197
	v_cndmask_b32_e64 v8, v203, v8, s[64:65]
	ds_read_b32 v197, v174 offset:496
	v_add_f32_e32 v9, v9, v198
	v_cndmask_b32_e64 v9, v203, v9, s[66:67]
	ds_read_b32 v198, v175 offset:496
	v_add_f32_e32 v10, v10, v199
	v_cndmask_b32_e64 v10, v203, v10, s[68:69]
	ds_read_b32 v199, v176 offset:496
	v_add_f32_e32 v11, v11, v189
	v_cndmask_b32_e64 v11, v203, v11, s[70:71]
	ds_read_b32 v189, v177 offset:496
	v_add_f32_e32 v12, v12, v190
	v_cndmask_b32_e64 v12, v203, v12, s[72:73]
	ds_read_b32 v190, v178 offset:496
	v_add_f32_e32 v13, v13, v191
	v_cndmask_b32_e64 v13, v203, v13, s[74:75]
	ds_read_b32 v191, v179 offset:496
	v_add_f32_e32 v14, v14, v192
	v_cndmask_b32_e64 v14, v203, v14, s[76:77]
	ds_read_b32 v192, v180 offset:496
	v_add_f32_e32 v15, v15, v193
	v_cndmask_b32_e64 v15, v203, v15, s[78:79]
	ds_read_b32 v193, v181 offset:496
	v_exp_f32_e32 v8, v8
	v_exp_f32_e32 v9, v9
	v_add_f32_e32 v232, v232, v8
	v_add_f32_e32 v233, v233, v9
	v_exp_f32_e32 v10, v10
	v_exp_f32_e32 v11, v11
	v_add_f32_e32 v232, v232, v10
	v_add_f32_e32 v233, v233, v11
	v_exp_f32_e32 v12, v12
	v_exp_f32_e32 v13, v13
	v_add_f32_e32 v232, v232, v12
	v_add_f32_e32 v233, v233, v13
	v_exp_f32_e32 v14, v14
	v_exp_f32_e32 v15, v15
	v_add_f32_e32 v232, v232, v14
	v_add_f32_e32 v233, v233, v15
	v_cvt_pk_bf16_f32 v8, v8, v9
	v_cvt_pk_bf16_f32 v9, v10, v11
	v_cvt_pk_bf16_f32 v10, v12, v13
	v_cvt_pk_bf16_f32 v11, v14, v15
	s_waitcnt lgkmcnt(11)
	s_nop 0
	v_mfma_f32_32x32x16_bf16 v[48:63], v[212:215], v[8:11], v[48:63]
	s_waitcnt lgkmcnt(10)
	v_mfma_f32_32x32x16_bf16 v[32:47], v[216:219], v[8:11], v[32:47]
	ds_read_b128 v[204:207], v249 offset:9280
	ds_read_b128 v[208:211], v249 offset:13888
	ds_read_b128 v[212:215], v249 offset:9312
	ds_read_b128 v[216:219], v249 offset:13920
	v_add_f32_e32 v16, v16, v194
	v_cndmask_b32_e64 v16, v203, v16, s[80:81]
	ds_read_b32 v194, v182 offset:496
	s_waitcnt lgkmcnt(14)
	v_add_f32_e32 v17, v17, v195
	v_cndmask_b32_e64 v17, v203, v17, s[82:83]
	ds_read_b32 v195, v183 offset:496
	s_waitcnt lgkmcnt(14)
	v_add_f32_e32 v18, v18, v196
	v_cndmask_b32_e64 v18, v203, v18, s[84:85]
	ds_read_b32 v196, v184 offset:496
	s_waitcnt lgkmcnt(14)
	v_add_f32_e32 v19, v19, v197
	v_cndmask_b32_e64 v19, v203, v19, s[86:87]
	ds_read_b32 v197, v185 offset:496
	s_waitcnt lgkmcnt(14)
	v_add_f32_e32 v20, v20, v198
	v_cndmask_b32_e64 v20, v203, v20, s[88:89]
	ds_read_b32 v198, v186 offset:496
	s_waitcnt lgkmcnt(14)
	v_add_f32_e32 v21, v21, v199
	v_cndmask_b32_e64 v21, v203, v21, s[90:91]
	s_waitcnt lgkmcnt(13)
	v_add_f32_e32 v22, v22, v189
	v_cndmask_b32_e64 v22, v203, v22, s[92:93]
	s_waitcnt lgkmcnt(12)
	v_add_f32_e32 v23, v23, v190
	v_cndmask_b32_e64 v23, v203, v23, s[94:95]
	v_exp_f32_e32 v16, v16
	v_exp_f32_e32 v17, v17
	v_add_f32_e32 v232, v232, v16
	v_add_f32_e32 v233, v233, v17
	v_exp_f32_e32 v18, v18
	v_exp_f32_e32 v19, v19
	v_add_f32_e32 v232, v232, v18
	v_add_f32_e32 v233, v233, v19
	v_exp_f32_e32 v20, v20
	v_exp_f32_e32 v21, v21
	v_add_f32_e32 v232, v232, v20
	v_add_f32_e32 v233, v233, v21
	v_exp_f32_e32 v22, v22
	v_exp_f32_e32 v23, v23
	v_add_f32_e32 v232, v232, v22
	v_add_f32_e32 v233, v233, v23
	v_cvt_pk_bf16_f32 v16, v16, v17
	v_cvt_pk_bf16_f32 v17, v18, v19
	v_cvt_pk_bf16_f32 v18, v20, v21
	v_cvt_pk_bf16_f32 v19, v22, v23
	s_waitcnt lgkmcnt(8)
	s_nop 0
	v_mfma_f32_32x32x16_bf16 v[48:63], v[204:207], v[16:19], v[48:63]
	s_waitcnt lgkmcnt(7)
	v_mfma_f32_32x32x16_bf16 v[32:47], v[208:211], v[16:19], v[32:47]
	v_add_f32_e32 v24, v24, v191
	v_cndmask_b32_e64 v24, v203, v24, s[96:97]
	v_add_f32_e32 v25, v25, v192
	v_cndmask_b32_e64 v25, v203, v25, s[40:41]
	v_add_f32_e32 v26, v26, v193
	v_cndmask_b32_e64 v26, v203, v26, s[38:39]
	s_waitcnt lgkmcnt(4)
	v_add_f32_e32 v27, v27, v194
	v_cndmask_b32_e64 v27, v203, v27, s[44:45]
	s_waitcnt lgkmcnt(3)
	v_add_f32_e32 v28, v28, v195
	v_cndmask_b32_e64 v28, v203, v28, s[4:5]
	s_waitcnt lgkmcnt(2)
	v_add_f32_e32 v29, v29, v196
	v_cndmask_b32_e64 v29, v203, v29, s[42:43]
	s_waitcnt lgkmcnt(1)
	v_add_f32_e32 v30, v30, v197
	v_cndmask_b32_e64 v30, v203, v30, s[50:51]
	s_waitcnt lgkmcnt(0)
	v_add_f32_e32 v31, v31, v198
	v_cndmask_b32_e64 v31, v203, v31, s[6:7]
	v_exp_f32_e32 v24, v24
	v_exp_f32_e32 v25, v25
	v_add_f32_e32 v232, v232, v24
	v_add_f32_e32 v233, v233, v25
	v_exp_f32_e32 v26, v26
	v_exp_f32_e32 v27, v27
	v_add_f32_e32 v232, v232, v26
	v_add_f32_e32 v233, v233, v27
	v_exp_f32_e32 v28, v28
	v_exp_f32_e32 v29, v29
	v_add_f32_e32 v232, v232, v28
	v_add_f32_e32 v233, v233, v29
	v_exp_f32_e32 v30, v30
	v_exp_f32_e32 v31, v31
	v_add_f32_e32 v232, v232, v30
	v_add_f32_e32 v233, v233, v31
	v_cvt_pk_bf16_f32 v24, v24, v25
	v_cvt_pk_bf16_f32 v25, v26, v27
	v_cvt_pk_bf16_f32 v26, v28, v29
	v_cvt_pk_bf16_f32 v27, v30, v31
	s_nop 1
	v_mfma_f32_32x32x16_bf16 v[48:63], v[212:215], v[24:27], v[48:63]
	v_mfma_f32_32x32x16_bf16 v[32:47], v[216:219], v[24:27], v[32:47]
	v_add_f32_e32 v232, v232, v233
	v_cmp_lt_f32_e32 vcc, s33, v232
	s_cbranch_vccz .Lna_nr4
	s_nop 15
	v_and_b32_e32 v243, 64, v237
	v_xor_b32_e32 v242, 32, v237
	v_add_u32_e32 v243, 64, v243
	v_cmp_lt_i32_e32 vcc, v242, v243
	s_nop 1
	v_cndmask_b32_e32 v242, v237, v242, vcc
	v_lshlrev_b32_e32 v242, 2, v242
	ds_bpermute_b32 v242, v242, v232
	s_waitcnt lgkmcnt(0)
	v_add_f32_e32 v242, v242, v232
	v_frexp_exp_i32_f32_e32 v242, v242
	v_max_i32_e32 v242, 1, v242
	v_add_u32_e32 v242, -1, v242
	v_cvt_f32_u32_e32 v242, v242
	v_exp_f32_e64 v243, -v242
	v_add_f32_e32 v188, v188, v242
	v_xor_b32_e32 v64, 0x80000000, v188
	v_mul_f32_e32 v187, v187, v243
	v_mul_f32_e32 v232, v232, v243
	v_mul_f32_e32 v32, v32, v243
	v_mul_f32_e32 v33, v33, v243
	v_mul_f32_e32 v34, v34, v243
	v_mul_f32_e32 v35, v35, v243
	v_mul_f32_e32 v36, v36, v243
	v_mul_f32_e32 v37, v37, v243
	v_mul_f32_e32 v38, v38, v243
	v_mul_f32_e32 v39, v39, v243
	v_mul_f32_e32 v40, v40, v243
	v_mul_f32_e32 v41, v41, v243
	v_mul_f32_e32 v42, v42, v243
	v_mul_f32_e32 v43, v43, v243
	v_mul_f32_e32 v44, v44, v243
	v_mul_f32_e32 v45, v45, v243
	v_mul_f32_e32 v46, v46, v243
	v_mul_f32_e32 v47, v47, v243
	v_mul_f32_e32 v48, v48, v243
	v_mul_f32_e32 v49, v49, v243
	v_mul_f32_e32 v50, v50, v243
	v_mul_f32_e32 v51, v51, v243
	v_mul_f32_e32 v52, v52, v243
	v_mul_f32_e32 v53, v53, v243
	v_mul_f32_e32 v54, v54, v243
	v_mul_f32_e32 v55, v55, v243
	v_mul_f32_e32 v56, v56, v243
	v_mul_f32_e32 v57, v57, v243
	v_mul_f32_e32 v58, v58, v243
	v_mul_f32_e32 v59, v59, v243
	v_mul_f32_e32 v60, v60, v243
	v_mul_f32_e32 v61, v61, v243
	v_mul_f32_e32 v62, v62, v243
	v_mul_f32_e32 v63, v63, v243
	v_mov_b32_e32 v65, v64
	v_mov_b32_e32 v66, v64
	v_mov_b32_e32 v67, v64
	v_mov_b32_e32 v68, v64
	v_mov_b32_e32 v69, v64
	v_mov_b32_e32 v70, v64
	v_mov_b32_e32 v71, v64
	v_mov_b32_e32 v72, v64
	v_mov_b32_e32 v73, v64
	v_mov_b32_e32 v74, v64
	v_mov_b32_e32 v75, v64
	v_mov_b32_e32 v76, v64
	v_mov_b32_e32 v77, v64
	v_mov_b32_e32 v78, v64
	v_mov_b32_e32 v79, v64

.Lna_it5:
	s_add_i32 s17, s37, 0x12000
	v_add3_u32 v248, s17, v146, v149
	v_add3_u32 v249, s17, v154, v146
	ds_read_b128 v[204:207], v248
	ds_read_b128 v[208:211], v248 offset:32
	ds_read_b128 v[212:215], v248 offset:64
	ds_read_b128 v[216:219], v248 offset:96
	v_lshl_add_u64 v[2:3], v[152:153], 0, v[200:201]
	v_add_co_u32_e32 v4, vcc, 0x12d00000, v2
	v_lshl_add_u64 v[0:1], v[150:151], 0, v[200:201]
	s_nop 0
	v_addc_co_u32_e32 v5, vcc, 0, v3, vcc
	v_add_co_u32_e32 v6, vcc, 0x12e00000, v2
	global_load_dwordx4 v[80:83], v[0:1], off offset:-256
	global_load_dwordx4 v[84:87], v[0:1], off offset:-128
	v_addc_co_u32_e32 v7, vcc, 0, v3, vcc
	global_load_dwordx4 v[88:91], v[4:5], off offset:128
	global_load_dwordx4 v[92:95], v[6:7], off offset:128
	v_add_co_u32_e32 v4, vcc, 0x12f00000, v2
	global_load_dwordx4 v[220:223], v[0:1], off
	global_load_dwordx4 v[224:227], v[0:1], off offset:128
	v_addc_co_u32_e32 v5, vcc, 0, v3, vcc
	v_add_co_u32_e32 v0, vcc, 0x13000000, v2
	s_nop 1
	v_addc_co_u32_e32 v1, vcc, 0, v3, vcc
	global_load_dwordx4 v[228:231], v[4:5], off offset:128
	global_load_dwordx4 v[244:247], v[0:1], off offset:128
	v_lshl_add_u64 v[152:153], v[152:153], 0, s[26:27]
	v_lshl_add_u64 v[150:151], v[150:151], 0, s[28:29]
	v_mov_b32_e32 v203, 0xf149f2ca
	ds_read_b32 v189, v155 offset:620
	ds_read_b32 v190, v156 offset:620
	ds_read_b32 v191, v157 offset:620
	ds_read_b32 v192, v158 offset:620
	ds_read_b32 v193, v159 offset:620
	ds_read_b32 v194, v160 offset:620
	ds_read_b32 v195, v161 offset:620
	ds_read_b32 v196, v162 offset:620
	ds_read_b32 v197, v163 offset:620
	ds_read_b32 v198, v164 offset:620
	ds_read_b32 v199, v165 offset:620
	s_waitcnt lgkmcnt(14)
	v_mfma_f32_32x32x16_bf16 v[0:15], v[204:207], v[96:99], v[64:79]
	s_waitcnt lgkmcnt(13)
	v_mfma_f32_32x32x16_bf16 v[0:15], v[208:211], v[100:103], v[0:15]
	s_waitcnt lgkmcnt(12)
	v_mfma_f32_32x32x16_bf16 v[0:15], v[212:215], v[104:107], v[0:15]
	s_waitcnt lgkmcnt(11)
	v_mfma_f32_32x32x16_bf16 v[0:15], v[216:219], v[108:111], v[0:15]
	ds_read_b128 v[204:207], v248 offset:4608
	ds_read_b128 v[208:211], v248 offset:4640
	ds_read_b128 v[212:215], v248 offset:4672
	ds_read_b128 v[216:219], v248 offset:4704
	s_waitcnt lgkmcnt(3)
	v_mfma_f32_32x32x16_bf16 v[16:31], v[204:207], v[96:99], v[64:79]
	s_nop 5
	v_add_f32_e32 v0, v0, v189
	v_cndmask_b32_e64 v0, v203, v0, s[2:3]
	ds_read_b32 v189, v166 offset:620
	v_add_f32_e32 v1, v1, v190
	v_cndmask_b32_e64 v1, v203, v1, s[48:49]
	ds_read_b32 v190, v167 offset:620
	s_waitcnt lgkmcnt(4)
	v_mfma_f32_32x32x16_bf16 v[16:31], v[208:211], v[100:103], v[16:31]
	v_add_f32_e32 v2, v2, v191
	v_cndmask_b32_e64 v2, v203, v2, s[52:53]
	ds_read_b32 v191, v168 offset:620
	v_add_f32_e32 v3, v3, v192
	v_cndmask_b32_e64 v3, v203, v3, s[54:55]
	ds_read_b32 v192, v169 offset:620
	s_waitcnt lgkmcnt(5)
	v_mfma_f32_32x32x16_bf16 v[16:31], v[212:215], v[104:107], v[16:31]
	v_add_f32_e32 v4, v4, v193
	v_cndmask_b32_e64 v4, v203, v4, s[56:57]
	ds_read_b32 v193, v170 offset:620
	v_add_f32_e32 v5, v5, v194
	v_cndmask_b32_e64 v5, v203, v5, s[58:59]
	ds_read_b32 v194, v171 offset:620
	s_waitcnt lgkmcnt(6)
	v_mfma_f32_32x32x16_bf16 v[16:31], v[216:219], v[108:111], v[16:31]
	ds_read_b128 v[204:207], v249 offset:9216
	ds_read_b128 v[208:211], v249 offset:13824
	ds_read_b128 v[212:215], v249 offset:9248
	ds_read_b128 v[216:219], v249 offset:13856
	v_add_f32_e32 v6, v6, v195
	v_cndmask_b32_e64 v6, v203, v6, s[60:61]
	ds_read_b32 v195, v172 offset:620
	v_add_f32_e32 v7, v7, v196
	v_cndmask_b32_e64 v7, v203, v7, s[62:63]
	ds_read_b32 v196, v173 offset:620
	v_exp_f32_e32 v0, v0
	v_exp_f32_e32 v1, v1
	v_exp_f32_e32 v2, v2
	v_exp_f32_e32 v3, v3
	v_add_f32_e32 v232, v0, v2
	v_add_f32_e32 v233, v1, v3
	v_exp_f32_e32 v4, v4
	v_exp_f32_e32 v5, v5
	v_add_f32_e32 v232, v232, v4
	v_add_f32_e32 v233, v233, v5
	v_exp_f32_e32 v6, v6
	v_exp_f32_e32 v7, v7
	v_add_f32_e32 v232, v232, v6
	v_add_f32_e32 v233, v233, v7
	v_cvt_pk_bf16_f32 v0, v0, v1
	v_cvt_pk_bf16_f32 v1, v2, v3
	v_cvt_pk_bf16_f32 v2, v4, v5
	v_cvt_pk_bf16_f32 v3, v6, v7
	s_waitcnt lgkmcnt(5)
	s_nop 0
	v_mfma_f32_32x32x16_bf16 v[48:63], v[204:207], v[0:3], v[48:63]
	s_waitcnt lgkmcnt(4)
	v_mfma_f32_32x32x16_bf16 v[32:47], v[208:211], v[0:3], v[32:47]
	v_add_f32_e32 v8, v8, v197
	v_cndmask_b32_e64 v8, v203, v8, s[64:65]
	ds_read_b32 v197, v174 offset:620
	v_add_f32_e32 v9, v9, v198
	v_cndmask_b32_e64 v9, v203, v9, s[66:67]
	ds_read_b32 v198, v175 offset:620
	v_add_f32_e32 v10, v10, v199
	v_cndmask_b32_e64 v10, v203, v10, s[68:69]
	ds_read_b32 v199, v176 offset:620
	v_add_f32_e32 v11, v11, v189
	v_cndmask_b32_e64 v11, v203, v11, s[70:71]
	ds_read_b32 v189, v177 offset:620
	v_add_f32_e32 v12, v12, v190
	v_cndmask_b32_e64 v12, v203, v12, s[72:73]
	ds_read_b32 v190, v178 offset:620
	v_add_f32_e32 v13, v13, v191
	v_cndmask_b32_e64 v13, v203, v13, s[74:75]
	ds_read_b32 v191, v179 offset:620
	v_add_f32_e32 v14, v14, v192
	v_cndmask_b32_e64 v14, v203, v14, s[76:77]
	ds_read_b32 v192, v180 offset:620
	v_add_f32_e32 v15, v15, v193
	v_cndmask_b32_e64 v15, v203, v15, s[78:79]
	ds_read_b32 v193, v181 offset:620
	v_exp_f32_e32 v8, v8
	v_exp_f32_e32 v9, v9
	v_add_f32_e32 v232, v232, v8
	v_add_f32_e32 v233, v233, v9
	v_exp_f32_e32 v10, v10
	v_exp_f32_e32 v11, v11
	v_add_f32_e32 v232, v232, v10
	v_add_f32_e32 v233, v233, v11
	v_exp_f32_e32 v12, v12
	v_exp_f32_e32 v13, v13
	v_add_f32_e32 v232, v232, v12
	v_add_f32_e32 v233, v233, v13
	v_exp_f32_e32 v14, v14
	v_exp_f32_e32 v15, v15
	v_add_f32_e32 v232, v232, v14
	v_add_f32_e32 v233, v233, v15
	v_cvt_pk_bf16_f32 v8, v8, v9
	v_cvt_pk_bf16_f32 v9, v10, v11
	v_cvt_pk_bf16_f32 v10, v12, v13
	v_cvt_pk_bf16_f32 v11, v14, v15
	s_waitcnt lgkmcnt(11)
	s_nop 0
	v_mfma_f32_32x32x16_bf16 v[48:63], v[212:215], v[8:11], v[48:63]
	s_waitcnt lgkmcnt(10)
	v_mfma_f32_32x32x16_bf16 v[32:47], v[216:219], v[8:11], v[32:47]
	ds_read_b128 v[204:207], v249 offset:9280
	ds_read_b128 v[208:211], v249 offset:13888
	ds_read_b128 v[212:215], v249 offset:9312
	ds_read_b128 v[216:219], v249 offset:13920
	v_add_f32_e32 v16, v16, v194
	v_cndmask_b32_e64 v16, v203, v16, s[80:81]
	ds_read_b32 v194, v182 offset:620
	s_waitcnt lgkmcnt(14)
	v_add_f32_e32 v17, v17, v195
	v_cndmask_b32_e64 v17, v203, v17, s[82:83]
	ds_read_b32 v195, v183 offset:620
	s_waitcnt lgkmcnt(14)
	v_add_f32_e32 v18, v18, v196
	v_cndmask_b32_e64 v18, v203, v18, s[84:85]
	ds_read_b32 v196, v184 offset:620
	s_waitcnt lgkmcnt(14)
	v_add_f32_e32 v19, v19, v197
	v_cndmask_b32_e64 v19, v203, v19, s[86:87]
	ds_read_b32 v197, v185 offset:620
	s_waitcnt lgkmcnt(14)
	v_add_f32_e32 v20, v20, v198
	v_cndmask_b32_e64 v20, v203, v20, s[88:89]
	ds_read_b32 v198, v186 offset:620
	s_waitcnt lgkmcnt(14)
	v_add_f32_e32 v21, v21, v199
	v_cndmask_b32_e64 v21, v203, v21, s[90:91]
	s_waitcnt lgkmcnt(13)
	v_add_f32_e32 v22, v22, v189
	v_cndmask_b32_e64 v22, v203, v22, s[92:93]
	s_waitcnt lgkmcnt(12)
	v_add_f32_e32 v23, v23, v190
	v_cndmask_b32_e64 v23, v203, v23, s[94:95]
	v_exp_f32_e32 v16, v16
	v_exp_f32_e32 v17, v17
	v_add_f32_e32 v232, v232, v16
	v_add_f32_e32 v233, v233, v17
	v_exp_f32_e32 v18, v18
	v_exp_f32_e32 v19, v19
	v_add_f32_e32 v232, v232, v18
	v_add_f32_e32 v233, v233, v19
	v_exp_f32_e32 v20, v20
	v_exp_f32_e32 v21, v21
	v_add_f32_e32 v232, v232, v20
	v_add_f32_e32 v233, v233, v21
	v_exp_f32_e32 v22, v22
	v_exp_f32_e32 v23, v23
	v_add_f32_e32 v232, v232, v22
	v_add_f32_e32 v233, v233, v23
	v_cvt_pk_bf16_f32 v16, v16, v17
	v_cvt_pk_bf16_f32 v17, v18, v19
	v_cvt_pk_bf16_f32 v18, v20, v21
	v_cvt_pk_bf16_f32 v19, v22, v23
	s_waitcnt lgkmcnt(8)
	s_nop 0
	v_mfma_f32_32x32x16_bf16 v[48:63], v[204:207], v[16:19], v[48:63]
	s_waitcnt lgkmcnt(7)
	v_mfma_f32_32x32x16_bf16 v[32:47], v[208:211], v[16:19], v[32:47]
	v_add_f32_e32 v24, v24, v191
	v_cndmask_b32_e64 v24, v203, v24, s[96:97]
	v_add_f32_e32 v25, v25, v192
	v_cndmask_b32_e64 v25, v203, v25, s[40:41]
	v_add_f32_e32 v26, v26, v193
	v_cndmask_b32_e64 v26, v203, v26, s[38:39]
	s_waitcnt lgkmcnt(4)
	v_add_f32_e32 v27, v27, v194
	v_cndmask_b32_e64 v27, v203, v27, s[44:45]
	s_waitcnt lgkmcnt(3)
	v_add_f32_e32 v28, v28, v195
	v_cndmask_b32_e64 v28, v203, v28, s[4:5]
	s_waitcnt lgkmcnt(2)
	v_add_f32_e32 v29, v29, v196
	v_cndmask_b32_e64 v29, v203, v29, s[42:43]
	s_waitcnt lgkmcnt(1)
	v_add_f32_e32 v30, v30, v197
	v_cndmask_b32_e64 v30, v203, v30, s[50:51]
	s_waitcnt lgkmcnt(0)
	v_add_f32_e32 v31, v31, v198
	v_cndmask_b32_e64 v31, v203, v31, s[6:7]
	v_exp_f32_e32 v24, v24
	v_exp_f32_e32 v25, v25
	v_add_f32_e32 v232, v232, v24
	v_add_f32_e32 v233, v233, v25
	v_exp_f32_e32 v26, v26
	v_exp_f32_e32 v27, v27
	v_add_f32_e32 v232, v232, v26
	v_add_f32_e32 v233, v233, v27
	v_exp_f32_e32 v28, v28
	v_exp_f32_e32 v29, v29
	v_add_f32_e32 v232, v232, v28
	v_add_f32_e32 v233, v233, v29
	v_exp_f32_e32 v30, v30
	v_exp_f32_e32 v31, v31
	v_add_f32_e32 v232, v232, v30
	v_add_f32_e32 v233, v233, v31
	v_cvt_pk_bf16_f32 v24, v24, v25
	v_cvt_pk_bf16_f32 v25, v26, v27
	v_cvt_pk_bf16_f32 v26, v28, v29
	v_cvt_pk_bf16_f32 v27, v30, v31
	s_nop 1
	v_mfma_f32_32x32x16_bf16 v[48:63], v[212:215], v[24:27], v[48:63]
	v_mfma_f32_32x32x16_bf16 v[32:47], v[216:219], v[24:27], v[32:47]
	v_add_f32_e32 v232, v232, v233
	v_cmp_lt_f32_e32 vcc, s33, v232
	s_cbranch_vccz .Lna_nr5
	s_nop 15
	v_and_b32_e32 v243, 64, v237
	v_xor_b32_e32 v242, 32, v237
	v_add_u32_e32 v243, 64, v243
	v_cmp_lt_i32_e32 vcc, v242, v243
	s_nop 1
	v_cndmask_b32_e32 v242, v237, v242, vcc
	v_lshlrev_b32_e32 v242, 2, v242
	ds_bpermute_b32 v242, v242, v232
	s_waitcnt lgkmcnt(0)
	v_add_f32_e32 v242, v242, v232
	v_frexp_exp_i32_f32_e32 v242, v242
	v_max_i32_e32 v242, 1, v242
	v_add_u32_e32 v242, -1, v242
	v_cvt_f32_u32_e32 v242, v242
	v_exp_f32_e64 v243, -v242
	v_add_f32_e32 v188, v188, v242
	v_xor_b32_e32 v64, 0x80000000, v188
	v_mul_f32_e32 v187, v187, v243
	v_mul_f32_e32 v232, v232, v243
	v_mul_f32_e32 v32, v32, v243
	v_mul_f32_e32 v33, v33, v243
	v_mul_f32_e32 v34, v34, v243
	v_mul_f32_e32 v35, v35, v243
	v_mul_f32_e32 v36, v36, v243
	v_mul_f32_e32 v37, v37, v243
	v_mul_f32_e32 v38, v38, v243
	v_mul_f32_e32 v39, v39, v243
	v_mul_f32_e32 v40, v40, v243
	v_mul_f32_e32 v41, v41, v243
	v_mul_f32_e32 v42, v42, v243
	v_mul_f32_e32 v43, v43, v243
	v_mul_f32_e32 v44, v44, v243
	v_mul_f32_e32 v45, v45, v243
	v_mul_f32_e32 v46, v46, v243
	v_mul_f32_e32 v47, v47, v243
	v_mul_f32_e32 v48, v48, v243
	v_mul_f32_e32 v49, v49, v243
	v_mul_f32_e32 v50, v50, v243
	v_mul_f32_e32 v51, v51, v243
	v_mul_f32_e32 v52, v52, v243
	v_mul_f32_e32 v53, v53, v243
	v_mul_f32_e32 v54, v54, v243
	v_mul_f32_e32 v55, v55, v243
	v_mul_f32_e32 v56, v56, v243
	v_mul_f32_e32 v57, v57, v243
	v_mul_f32_e32 v58, v58, v243
	v_mul_f32_e32 v59, v59, v243
	v_mul_f32_e32 v60, v60, v243
	v_mul_f32_e32 v61, v61, v243
	v_mul_f32_e32 v62, v62, v243
	v_mul_f32_e32 v63, v63, v243
	v_mov_b32_e32 v65, v64
	v_mov_b32_e32 v66, v64
	v_mov_b32_e32 v67, v64
	v_mov_b32_e32 v68, v64
	v_mov_b32_e32 v69, v64
	v_mov_b32_e32 v70, v64
	v_mov_b32_e32 v71, v64
	v_mov_b32_e32 v72, v64
	v_mov_b32_e32 v73, v64
	v_mov_b32_e32 v74, v64
	v_mov_b32_e32 v75, v64
	v_mov_b32_e32 v76, v64
	v_mov_b32_e32 v77, v64
	v_mov_b32_e32 v78, v64
	v_mov_b32_e32 v79, v64

.Lna_it6:
	s_add_i32 s17, s37, 0x0
	v_add3_u32 v248, s17, v146, v149
	v_add3_u32 v249, s17, v154, v146
	ds_read_b128 v[204:207], v248
	ds_read_b128 v[208:211], v248 offset:32
	ds_read_b128 v[212:215], v248 offset:64
	ds_read_b128 v[216:219], v248 offset:96
	v_mov_b32_e32 v203, 0xf149f2ca
	ds_read_b32 v189, v155 offset:744
	ds_read_b32 v190, v156 offset:744
	ds_read_b32 v191, v157 offset:744
	ds_read_b32 v192, v158 offset:744
	ds_read_b32 v193, v159 offset:744
	ds_read_b32 v194, v160 offset:744
	ds_read_b32 v195, v161 offset:744
	ds_read_b32 v196, v162 offset:744
	ds_read_b32 v197, v163 offset:744
	ds_read_b32 v198, v164 offset:744
	ds_read_b32 v199, v165 offset:744
	s_waitcnt lgkmcnt(14)
	v_mfma_f32_32x32x16_bf16 v[0:15], v[204:207], v[96:99], v[64:79]
	s_waitcnt lgkmcnt(13)
	v_mfma_f32_32x32x16_bf16 v[0:15], v[208:211], v[100:103], v[0:15]
	s_waitcnt lgkmcnt(12)
	v_mfma_f32_32x32x16_bf16 v[0:15], v[212:215], v[104:107], v[0:15]
	s_waitcnt lgkmcnt(11)
	v_mfma_f32_32x32x16_bf16 v[0:15], v[216:219], v[108:111], v[0:15]
	ds_read_b128 v[204:207], v248 offset:4608
	ds_read_b128 v[208:211], v248 offset:4640
	ds_read_b128 v[212:215], v248 offset:4672
	ds_read_b128 v[216:219], v248 offset:4704
	s_waitcnt lgkmcnt(3)
	v_mfma_f32_32x32x16_bf16 v[16:31], v[204:207], v[96:99], v[64:79]
	s_nop 5
	v_add_f32_e32 v0, v0, v189
	v_cndmask_b32_e64 v0, v203, v0, s[2:3]
	ds_read_b32 v189, v166 offset:744
	v_add_f32_e32 v1, v1, v190
	v_cndmask_b32_e64 v1, v203, v1, s[48:49]
	ds_read_b32 v190, v167 offset:744
	s_waitcnt lgkmcnt(4)
	v_mfma_f32_32x32x16_bf16 v[16:31], v[208:211], v[100:103], v[16:31]
	v_add_f32_e32 v2, v2, v191
	v_cndmask_b32_e64 v2, v203, v2, s[52:53]
	ds_read_b32 v191, v168 offset:744
	v_add_f32_e32 v3, v3, v192
	v_cndmask_b32_e64 v3, v203, v3, s[54:55]
	ds_read_b32 v192, v169 offset:744
	s_waitcnt lgkmcnt(5)
	v_mfma_f32_32x32x16_bf16 v[16:31], v[212:215], v[104:107], v[16:31]
	v_add_f32_e32 v4, v4, v193
	v_cndmask_b32_e64 v4, v203, v4, s[56:57]
	ds_read_b32 v193, v170 offset:744
	v_add_f32_e32 v5, v5, v194
	v_cndmask_b32_e64 v5, v203, v5, s[58:59]
	ds_read_b32 v194, v171 offset:744
	s_waitcnt lgkmcnt(6)
	v_mfma_f32_32x32x16_bf16 v[16:31], v[216:219], v[108:111], v[16:31]
	ds_read_b128 v[204:207], v249 offset:9216
	ds_read_b128 v[208:211], v249 offset:13824
	ds_read_b128 v[212:215], v249 offset:9248
	ds_read_b128 v[216:219], v249 offset:13856
	v_add_f32_e32 v6, v6, v195
	v_cndmask_b32_e64 v6, v203, v6, s[60:61]
	ds_read_b32 v195, v172 offset:744
	v_add_f32_e32 v7, v7, v196
	v_cndmask_b32_e64 v7, v203, v7, s[62:63]
	ds_read_b32 v196, v173 offset:744
	v_exp_f32_e32 v0, v0
	v_exp_f32_e32 v1, v1
	v_exp_f32_e32 v2, v2
	v_exp_f32_e32 v3, v3
	v_add_f32_e32 v232, v0, v2
	v_add_f32_e32 v233, v1, v3
	v_exp_f32_e32 v4, v4
	v_exp_f32_e32 v5, v5
	v_add_f32_e32 v232, v232, v4
	v_add_f32_e32 v233, v233, v5
	v_exp_f32_e32 v6, v6
	v_exp_f32_e32 v7, v7
	v_add_f32_e32 v232, v232, v6
	v_add_f32_e32 v233, v233, v7
	v_cvt_pk_bf16_f32 v0, v0, v1
	v_cvt_pk_bf16_f32 v1, v2, v3
	v_cvt_pk_bf16_f32 v2, v4, v5
	v_cvt_pk_bf16_f32 v3, v6, v7
	s_waitcnt lgkmcnt(5)
	s_nop 0
	v_mfma_f32_32x32x16_bf16 v[48:63], v[204:207], v[0:3], v[48:63]
	s_waitcnt lgkmcnt(4)
	v_mfma_f32_32x32x16_bf16 v[32:47], v[208:211], v[0:3], v[32:47]
	v_add_f32_e32 v8, v8, v197
	v_cndmask_b32_e64 v8, v203, v8, s[64:65]
	ds_read_b32 v197, v174 offset:744
	v_add_f32_e32 v9, v9, v198
	v_cndmask_b32_e64 v9, v203, v9, s[66:67]
	ds_read_b32 v198, v175 offset:744
	v_add_f32_e32 v10, v10, v199
	v_cndmask_b32_e64 v10, v203, v10, s[68:69]
	ds_read_b32 v199, v176 offset:744
	v_add_f32_e32 v11, v11, v189
	v_cndmask_b32_e64 v11, v203, v11, s[70:71]
	ds_read_b32 v189, v177 offset:744
	v_add_f32_e32 v12, v12, v190
	v_cndmask_b32_e64 v12, v203, v12, s[72:73]
	ds_read_b32 v190, v178 offset:744
	v_add_f32_e32 v13, v13, v191
	v_cndmask_b32_e64 v13, v203, v13, s[74:75]
	ds_read_b32 v191, v179 offset:744
	v_add_f32_e32 v14, v14, v192
	v_cndmask_b32_e64 v14, v203, v14, s[76:77]
	ds_read_b32 v192, v180 offset:744
	v_add_f32_e32 v15, v15, v193
	v_cndmask_b32_e64 v15, v203, v15, s[78:79]
	ds_read_b32 v193, v181 offset:744
	v_exp_f32_e32 v8, v8
	v_exp_f32_e32 v9, v9
	v_add_f32_e32 v232, v232, v8
	v_add_f32_e32 v233, v233, v9
	v_exp_f32_e32 v10, v10
	v_exp_f32_e32 v11, v11
	v_add_f32_e32 v232, v232, v10
	v_add_f32_e32 v233, v233, v11
	v_exp_f32_e32 v12, v12
	v_exp_f32_e32 v13, v13
	v_add_f32_e32 v232, v232, v12
	v_add_f32_e32 v233, v233, v13
	v_exp_f32_e32 v14, v14
	v_exp_f32_e32 v15, v15
	v_add_f32_e32 v232, v232, v14
	v_add_f32_e32 v233, v233, v15
	v_cvt_pk_bf16_f32 v8, v8, v9
	v_cvt_pk_bf16_f32 v9, v10, v11
	v_cvt_pk_bf16_f32 v10, v12, v13
	v_cvt_pk_bf16_f32 v11, v14, v15
	s_waitcnt lgkmcnt(11)
	s_nop 0
	v_mfma_f32_32x32x16_bf16 v[48:63], v[212:215], v[8:11], v[48:63]
	s_waitcnt lgkmcnt(10)
	v_mfma_f32_32x32x16_bf16 v[32:47], v[216:219], v[8:11], v[32:47]
	ds_read_b128 v[204:207], v249 offset:9280
	ds_read_b128 v[208:211], v249 offset:13888
	ds_read_b128 v[212:215], v249 offset:9312
	ds_read_b128 v[216:219], v249 offset:13920
	v_add_f32_e32 v16, v16, v194
	v_cndmask_b32_e64 v16, v203, v16, s[80:81]
	ds_read_b32 v194, v182 offset:744
	s_waitcnt lgkmcnt(14)
	v_add_f32_e32 v17, v17, v195
	v_cndmask_b32_e64 v17, v203, v17, s[82:83]
	ds_read_b32 v195, v183 offset:744
	s_waitcnt lgkmcnt(14)
	v_add_f32_e32 v18, v18, v196
	v_cndmask_b32_e64 v18, v203, v18, s[84:85]
	ds_read_b32 v196, v184 offset:744
	s_waitcnt lgkmcnt(14)
	v_add_f32_e32 v19, v19, v197
	v_cndmask_b32_e64 v19, v203, v19, s[86:87]
	ds_read_b32 v197, v185 offset:744
	s_waitcnt lgkmcnt(14)
	v_add_f32_e32 v20, v20, v198
	v_cndmask_b32_e64 v20, v203, v20, s[88:89]
	ds_read_b32 v198, v186 offset:744
	s_waitcnt lgkmcnt(14)
	v_add_f32_e32 v21, v21, v199
	v_cndmask_b32_e64 v21, v203, v21, s[90:91]
	s_waitcnt lgkmcnt(13)
	v_add_f32_e32 v22, v22, v189
	v_cndmask_b32_e64 v22, v203, v22, s[92:93]
	s_waitcnt lgkmcnt(12)
	v_add_f32_e32 v23, v23, v190
	v_cndmask_b32_e64 v23, v203, v23, s[94:95]
	v_exp_f32_e32 v16, v16
	v_exp_f32_e32 v17, v17
	v_add_f32_e32 v232, v232, v16
	v_add_f32_e32 v233, v233, v17
	v_exp_f32_e32 v18, v18
	v_exp_f32_e32 v19, v19
	v_add_f32_e32 v232, v232, v18
	v_add_f32_e32 v233, v233, v19
	v_exp_f32_e32 v20, v20
	v_exp_f32_e32 v21, v21
	v_add_f32_e32 v232, v232, v20
	v_add_f32_e32 v233, v233, v21
	v_exp_f32_e32 v22, v22
	v_exp_f32_e32 v23, v23
	v_add_f32_e32 v232, v232, v22
	v_add_f32_e32 v233, v233, v23
	v_cvt_pk_bf16_f32 v16, v16, v17
	v_cvt_pk_bf16_f32 v17, v18, v19
	v_cvt_pk_bf16_f32 v18, v20, v21
	v_cvt_pk_bf16_f32 v19, v22, v23
	s_waitcnt lgkmcnt(8)
	s_nop 0
	v_mfma_f32_32x32x16_bf16 v[48:63], v[204:207], v[16:19], v[48:63]
	s_waitcnt lgkmcnt(7)
	v_mfma_f32_32x32x16_bf16 v[32:47], v[208:211], v[16:19], v[32:47]
	v_add_f32_e32 v24, v24, v191
	v_cndmask_b32_e64 v24, v203, v24, s[96:97]
	v_add_f32_e32 v25, v25, v192
	v_cndmask_b32_e64 v25, v203, v25, s[40:41]
	v_add_f32_e32 v26, v26, v193
	v_cndmask_b32_e64 v26, v203, v26, s[38:39]
	s_waitcnt lgkmcnt(4)
	v_add_f32_e32 v27, v27, v194
	v_cndmask_b32_e64 v27, v203, v27, s[44:45]
	s_waitcnt lgkmcnt(3)
	v_add_f32_e32 v28, v28, v195
	v_cndmask_b32_e64 v28, v203, v28, s[4:5]
	s_waitcnt lgkmcnt(2)
	v_add_f32_e32 v29, v29, v196
	v_cndmask_b32_e64 v29, v203, v29, s[42:43]
	s_waitcnt lgkmcnt(1)
	v_add_f32_e32 v30, v30, v197
	v_cndmask_b32_e64 v30, v203, v30, s[50:51]
	s_waitcnt lgkmcnt(0)
	v_add_f32_e32 v31, v31, v198
	v_cndmask_b32_e64 v31, v203, v31, s[6:7]
	v_exp_f32_e32 v24, v24
	v_exp_f32_e32 v25, v25
	v_add_f32_e32 v232, v232, v24
	v_add_f32_e32 v233, v233, v25
	v_exp_f32_e32 v26, v26
	v_exp_f32_e32 v27, v27
	v_add_f32_e32 v232, v232, v26
	v_add_f32_e32 v233, v233, v27
	v_exp_f32_e32 v28, v28
	v_exp_f32_e32 v29, v29
	v_add_f32_e32 v232, v232, v28
	v_add_f32_e32 v233, v233, v29
	v_exp_f32_e32 v30, v30
	v_exp_f32_e32 v31, v31
	v_add_f32_e32 v232, v232, v30
	v_add_f32_e32 v233, v233, v31
	v_cvt_pk_bf16_f32 v24, v24, v25
	v_cvt_pk_bf16_f32 v25, v26, v27
	v_cvt_pk_bf16_f32 v26, v28, v29
	v_cvt_pk_bf16_f32 v27, v30, v31
	s_nop 1
	v_mfma_f32_32x32x16_bf16 v[48:63], v[212:215], v[24:27], v[48:63]
	v_mfma_f32_32x32x16_bf16 v[32:47], v[216:219], v[24:27], v[32:47]
	v_add_f32_e32 v232, v232, v233
	v_cmp_lt_f32_e32 vcc, s33, v232
	s_cbranch_vccz .Lna_nr6
	s_nop 15
	v_and_b32_e32 v243, 64, v237
	v_xor_b32_e32 v242, 32, v237
	v_add_u32_e32 v243, 64, v243
	v_cmp_lt_i32_e32 vcc, v242, v243
	s_nop 1
	v_cndmask_b32_e32 v242, v237, v242, vcc
	v_lshlrev_b32_e32 v242, 2, v242
	ds_bpermute_b32 v242, v242, v232
	s_waitcnt lgkmcnt(0)
	v_add_f32_e32 v242, v242, v232
	v_frexp_exp_i32_f32_e32 v242, v242
	v_max_i32_e32 v242, 1, v242
	v_add_u32_e32 v242, -1, v242
	v_cvt_f32_u32_e32 v242, v242
	v_exp_f32_e64 v243, -v242
	v_add_f32_e32 v188, v188, v242
	v_xor_b32_e32 v64, 0x80000000, v188
	v_mul_f32_e32 v187, v187, v243
	v_mul_f32_e32 v232, v232, v243
	v_mul_f32_e32 v32, v32, v243
	v_mul_f32_e32 v33, v33, v243
	v_mul_f32_e32 v34, v34, v243
	v_mul_f32_e32 v35, v35, v243
	v_mul_f32_e32 v36, v36, v243
	v_mul_f32_e32 v37, v37, v243
	v_mul_f32_e32 v38, v38, v243
	v_mul_f32_e32 v39, v39, v243
	v_mul_f32_e32 v40, v40, v243
	v_mul_f32_e32 v41, v41, v243
	v_mul_f32_e32 v42, v42, v243
	v_mul_f32_e32 v43, v43, v243
	v_mul_f32_e32 v44, v44, v243
	v_mul_f32_e32 v45, v45, v243
	v_mul_f32_e32 v46, v46, v243
	v_mul_f32_e32 v47, v47, v243
	v_mul_f32_e32 v48, v48, v243
	v_mul_f32_e32 v49, v49, v243
	v_mul_f32_e32 v50, v50, v243
	v_mul_f32_e32 v51, v51, v243
	v_mul_f32_e32 v52, v52, v243
	v_mul_f32_e32 v53, v53, v243
	v_mul_f32_e32 v54, v54, v243
	v_mul_f32_e32 v55, v55, v243
	v_mul_f32_e32 v56, v56, v243
	v_mul_f32_e32 v57, v57, v243
	v_mul_f32_e32 v58, v58, v243
	v_mul_f32_e32 v59, v59, v243
	v_mul_f32_e32 v60, v60, v243
	v_mul_f32_e32 v61, v61, v243
	v_mul_f32_e32 v62, v62, v243
	v_mul_f32_e32 v63, v63, v243
	v_mov_b32_e32 v65, v64
	v_mov_b32_e32 v66, v64
	v_mov_b32_e32 v67, v64
	v_mov_b32_e32 v68, v64
	v_mov_b32_e32 v69, v64
	v_mov_b32_e32 v70, v64
	v_mov_b32_e32 v71, v64
	v_mov_b32_e32 v72, v64
	v_mov_b32_e32 v73, v64
	v_mov_b32_e32 v74, v64
	v_mov_b32_e32 v75, v64
	v_mov_b32_e32 v76, v64
	v_mov_b32_e32 v77, v64
	v_mov_b32_e32 v78, v64
	v_mov_b32_e32 v79, v64
.Lna_nr6:
	v_add_f32_e32 v187, v187, v232
	v_add_u32_e32 v242, 0x12000, v147
	s_waitcnt vmcnt(7)
	ds_write_b128 v242, v[80:83]
	s_waitcnt vmcnt(5)
	ds_write_b128 v242, v[88:91] offset:9216
	ds_write_b128 v242, v[84:87] offset:18432
	s_waitcnt vmcnt(4)
	ds_write_b128 v242, v[92:95] offset:27648
	s_waitcnt vmcnt(3)
	ds_write_b128 v242, v[220:223] offset:36864
	s_waitcnt vmcnt(1)
	ds_write_b128 v242, v[228:231] offset:46080
	ds_write_b128 v242, v[224:227] offset:55296
	s_waitcnt vmcnt(0)
	ds_write_b128 v242, v[244:247] offset:64512
	s_waitcnt lgkmcnt(0)
	s_barrier
.Lna_it7:
	s_add_i32 s17, s37, 0x12000
	v_add3_u32 v248, s17, v146, v149
	v_add3_u32 v249, s17, v154, v146
	ds_read_b128 v[204:207], v248
	ds_read_b128 v[208:211], v248 offset:32
	ds_read_b128 v[212:215], v248 offset:64
	ds_read_b128 v[216:219], v248 offset:96
	v_mov_b32_e32 v203, 0xf149f2ca
	ds_read_b32 v189, v155 offset:868
	ds_read_b32 v190, v156 offset:868
	ds_read_b32 v191, v157 offset:868
	ds_read_b32 v192, v158 offset:868
	ds_read_b32 v193, v159 offset:868
	ds_read_b32 v194, v160 offset:868
	ds_read_b32 v195, v161 offset:868
	ds_read_b32 v196, v162 offset:868
	ds_read_b32 v197, v163 offset:868
	ds_read_b32 v198, v164 offset:868
	ds_read_b32 v199, v165 offset:868
	s_waitcnt lgkmcnt(14)
	v_mfma_f32_32x32x16_bf16 v[0:15], v[204:207], v[96:99], v[64:79]
	s_waitcnt lgkmcnt(13)
	v_mfma_f32_32x32x16_bf16 v[0:15], v[208:211], v[100:103], v[0:15]
	s_waitcnt lgkmcnt(12)
	v_mfma_f32_32x32x16_bf16 v[0:15], v[212:215], v[104:107], v[0:15]
	s_waitcnt lgkmcnt(11)
	v_mfma_f32_32x32x16_bf16 v[0:15], v[216:219], v[108:111], v[0:15]
	ds_read_b128 v[204:207], v248 offset:4608
	ds_read_b128 v[208:211], v248 offset:4640
	ds_read_b128 v[212:215], v248 offset:4672
	ds_read_b128 v[216:219], v248 offset:4704
	s_waitcnt lgkmcnt(3)
	v_mfma_f32_32x32x16_bf16 v[16:31], v[204:207], v[96:99], v[64:79]
	s_nop 5
	v_add_f32_e32 v0, v0, v189
	v_cndmask_b32_e64 v0, v203, v0, s[2:3]
	ds_read_b32 v189, v166 offset:868
	v_add_f32_e32 v1, v1, v190
	v_cndmask_b32_e64 v1, v203, v1, s[48:49]
	ds_read_b32 v190, v167 offset:868
	s_waitcnt lgkmcnt(4)
	v_mfma_f32_32x32x16_bf16 v[16:31], v[208:211], v[100:103], v[16:31]
	v_add_f32_e32 v2, v2, v191
	v_cndmask_b32_e64 v2, v203, v2, s[52:53]
	ds_read_b32 v191, v168 offset:868
	v_add_f32_e32 v3, v3, v192
	v_cndmask_b32_e64 v3, v203, v3, s[54:55]
	ds_read_b32 v192, v169 offset:868
	s_waitcnt lgkmcnt(5)
	v_mfma_f32_32x32x16_bf16 v[16:31], v[212:215], v[104:107], v[16:31]
	v_add_f32_e32 v4, v4, v193
	v_cndmask_b32_e64 v4, v203, v4, s[56:57]
	ds_read_b32 v193, v170 offset:868
	v_add_f32_e32 v5, v5, v194
	v_cndmask_b32_e64 v5, v203, v5, s[58:59]
	ds_read_b32 v194, v171 offset:868
	s_waitcnt lgkmcnt(6)
	v_mfma_f32_32x32x16_bf16 v[16:31], v[216:219], v[108:111], v[16:31]
	ds_read_b128 v[204:207], v249 offset:9216
	ds_read_b128 v[208:211], v249 offset:13824
	ds_read_b128 v[212:215], v249 offset:9248
	ds_read_b128 v[216:219], v249 offset:13856
	v_add_f32_e32 v6, v6, v195
	v_cndmask_b32_e64 v6, v203, v6, s[60:61]
	ds_read_b32 v195, v172 offset:868
	v_add_f32_e32 v7, v7, v196
	v_cndmask_b32_e64 v7, v203, v7, s[62:63]
	ds_read_b32 v196, v173 offset:868
	v_exp_f32_e32 v0, v0
	v_exp_f32_e32 v1, v1
	v_exp_f32_e32 v2, v2
	v_exp_f32_e32 v3, v3
	v_add_f32_e32 v232, v0, v2
	v_add_f32_e32 v233, v1, v3
	v_exp_f32_e32 v4, v4
	v_exp_f32_e32 v5, v5
	v_add_f32_e32 v232, v232, v4
	v_add_f32_e32 v233, v233, v5
	v_exp_f32_e32 v6, v6
	v_exp_f32_e32 v7, v7
	v_add_f32_e32 v232, v232, v6
	v_add_f32_e32 v233, v233, v7
	v_cvt_pk_bf16_f32 v0, v0, v1
	v_cvt_pk_bf16_f32 v1, v2, v3
	v_cvt_pk_bf16_f32 v2, v4, v5
	v_cvt_pk_bf16_f32 v3, v6, v7
	s_waitcnt lgkmcnt(5)
	s_nop 0
	v_mfma_f32_32x32x16_bf16 v[48:63], v[204:207], v[0:3], v[48:63]
	s_waitcnt lgkmcnt(4)
	v_mfma_f32_32x32x16_bf16 v[32:47], v[208:211], v[0:3], v[32:47]
	v_add_f32_e32 v8, v8, v197
	v_cndmask_b32_e64 v8, v203, v8, s[64:65]
	ds_read_b32 v197, v174 offset:868
	v_add_f32_e32 v9, v9, v198
	v_cndmask_b32_e64 v9, v203, v9, s[66:67]
	ds_read_b32 v198, v175 offset:868
	v_add_f32_e32 v10, v10, v199
	v_cndmask_b32_e64 v10, v203, v10, s[68:69]
	ds_read_b32 v199, v176 offset:868
	v_add_f32_e32 v11, v11, v189
	v_cndmask_b32_e64 v11, v203, v11, s[70:71]
	ds_read_b32 v189, v177 offset:868
	v_add_f32_e32 v12, v12, v190
	v_cndmask_b32_e64 v12, v203, v12, s[72:73]
	ds_read_b32 v190, v178 offset:868
	v_add_f32_e32 v13, v13, v191
	v_cndmask_b32_e64 v13, v203, v13, s[74:75]
	ds_read_b32 v191, v179 offset:868
	v_add_f32_e32 v14, v14, v192
	v_cndmask_b32_e64 v14, v203, v14, s[76:77]
	ds_read_b32 v192, v180 offset:868
	v_add_f32_e32 v15, v15, v193
	v_cndmask_b32_e64 v15, v203, v15, s[78:79]
	ds_read_b32 v193, v181 offset:868
	v_exp_f32_e32 v8, v8
	v_exp_f32_e32 v9, v9
	v_add_f32_e32 v232, v232, v8
	v_add_f32_e32 v233, v233, v9
	v_exp_f32_e32 v10, v10
	v_exp_f32_e32 v11, v11
	v_add_f32_e32 v232, v232, v10
	v_add_f32_e32 v233, v233, v11
	v_exp_f32_e32 v12, v12
	v_exp_f32_e32 v13, v13
	v_add_f32_e32 v232, v232, v12
	v_add_f32_e32 v233, v233, v13
	v_exp_f32_e32 v14, v14
	v_exp_f32_e32 v15, v15
	v_add_f32_e32 v232, v232, v14
	v_add_f32_e32 v233, v233, v15
	v_cvt_pk_bf16_f32 v8, v8, v9
	v_cvt_pk_bf16_f32 v9, v10, v11
	v_cvt_pk_bf16_f32 v10, v12, v13
	v_cvt_pk_bf16_f32 v11, v14, v15
	s_waitcnt lgkmcnt(11)
	s_nop 0
	v_mfma_f32_32x32x16_bf16 v[48:63], v[212:215], v[8:11], v[48:63]
	s_waitcnt lgkmcnt(10)
	v_mfma_f32_32x32x16_bf16 v[32:47], v[216:219], v[8:11], v[32:47]
	ds_read_b128 v[204:207], v249 offset:9280
	ds_read_b128 v[208:211], v249 offset:13888
	ds_read_b128 v[212:215], v249 offset:9312
	ds_read_b128 v[216:219], v249 offset:13920
	v_add_f32_e32 v16, v16, v194
	v_cndmask_b32_e64 v16, v203, v16, s[80:81]
	ds_read_b32 v194, v182 offset:868
	s_waitcnt lgkmcnt(14)
	v_add_f32_e32 v17, v17, v195
	v_cndmask_b32_e64 v17, v203, v17, s[82:83]
	ds_read_b32 v195, v183 offset:868
	s_waitcnt lgkmcnt(14)
	v_add_f32_e32 v18, v18, v196
	v_cndmask_b32_e64 v18, v203, v18, s[84:85]
	ds_read_b32 v196, v184 offset:868
	s_waitcnt lgkmcnt(14)
	v_add_f32_e32 v19, v19, v197
	v_cndmask_b32_e64 v19, v203, v19, s[86:87]
	ds_read_b32 v197, v185 offset:868
	s_waitcnt lgkmcnt(14)
	v_add_f32_e32 v20, v20, v198
	v_cndmask_b32_e64 v20, v203, v20, s[88:89]
	ds_read_b32 v198, v186 offset:868
	s_waitcnt lgkmcnt(14)
	v_add_f32_e32 v21, v21, v199
	v_cndmask_b32_e64 v21, v203, v21, s[90:91]
	s_waitcnt lgkmcnt(13)
	v_add_f32_e32 v22, v22, v189
	v_cndmask_b32_e64 v22, v203, v22, s[92:93]
	s_waitcnt lgkmcnt(12)
	v_add_f32_e32 v23, v23, v190
	v_cndmask_b32_e64 v23, v203, v23, s[94:95]
	v_exp_f32_e32 v16, v16
	v_exp_f32_e32 v17, v17
	v_add_f32_e32 v232, v232, v16
	v_add_f32_e32 v233, v233, v17
	v_exp_f32_e32 v18, v18
	v_exp_f32_e32 v19, v19
	v_add_f32_e32 v232, v232, v18
	v_add_f32_e32 v233, v233, v19
	v_exp_f32_e32 v20, v20
	v_exp_f32_e32 v21, v21
	v_add_f32_e32 v232, v232, v20
	v_add_f32_e32 v233, v233, v21
	v_exp_f32_e32 v22, v22
	v_exp_f32_e32 v23, v23
	v_add_f32_e32 v232, v232, v22
	v_add_f32_e32 v233, v233, v23
	v_cvt_pk_bf16_f32 v16, v16, v17
	v_cvt_pk_bf16_f32 v17, v18, v19
	v_cvt_pk_bf16_f32 v18, v20, v21
	v_cvt_pk_bf16_f32 v19, v22, v23
	s_waitcnt lgkmcnt(8)
	s_nop 0
	v_mfma_f32_32x32x16_bf16 v[48:63], v[204:207], v[16:19], v[48:63]
	s_waitcnt lgkmcnt(7)
	v_mfma_f32_32x32x16_bf16 v[32:47], v[208:211], v[16:19], v[32:47]
	v_add_f32_e32 v24, v24, v191
	v_cndmask_b32_e64 v24, v203, v24, s[96:97]
	v_add_f32_e32 v25, v25, v192
	v_cndmask_b32_e64 v25, v203, v25, s[40:41]
	v_add_f32_e32 v26, v26, v193
	v_cndmask_b32_e64 v26, v203, v26, s[38:39]
	s_waitcnt lgkmcnt(4)
	v_add_f32_e32 v27, v27, v194
	v_cndmask_b32_e64 v27, v203, v27, s[44:45]
	s_waitcnt lgkmcnt(3)
	v_add_f32_e32 v28, v28, v195
	v_cndmask_b32_e64 v28, v203, v28, s[4:5]
	s_waitcnt lgkmcnt(2)
	v_add_f32_e32 v29, v29, v196
	v_cndmask_b32_e64 v29, v203, v29, s[42:43]
	s_waitcnt lgkmcnt(1)
	v_add_f32_e32 v30, v30, v197
	v_cndmask_b32_e64 v30, v203, v30, s[50:51]
	s_waitcnt lgkmcnt(0)
	v_add_f32_e32 v31, v31, v198
	v_cndmask_b32_e64 v31, v203, v31, s[6:7]
	v_exp_f32_e32 v24, v24
	v_exp_f32_e32 v25, v25
	v_add_f32_e32 v232, v232, v24
	v_add_f32_e32 v233, v233, v25
	v_exp_f32_e32 v26, v26
	v_exp_f32_e32 v27, v27
	v_add_f32_e32 v232, v232, v26
	v_add_f32_e32 v233, v233, v27
	v_exp_f32_e32 v28, v28
	v_exp_f32_e32 v29, v29
	v_add_f32_e32 v232, v232, v28
	v_add_f32_e32 v233, v233, v29
	v_exp_f32_e32 v30, v30
	v_exp_f32_e32 v31, v31
	v_add_f32_e32 v232, v232, v30
	v_add_f32_e32 v233, v233, v31
	v_cvt_pk_bf16_f32 v24, v24, v25
	v_cvt_pk_bf16_f32 v25, v26, v27
	v_cvt_pk_bf16_f32 v26, v28, v29
	v_cvt_pk_bf16_f32 v27, v30, v31
	s_nop 1
	v_mfma_f32_32x32x16_bf16 v[48:63], v[212:215], v[24:27], v[48:63]
	v_mfma_f32_32x32x16_bf16 v[32:47], v[216:219], v[24:27], v[32:47]
	v_add_f32_e32 v232, v232, v233
	v_cmp_lt_f32_e32 vcc, s33, v232
	s_cbranch_vccz .Lna_nr7
	s_nop 15
	v_and_b32_e32 v243, 64, v237
	v_xor_b32_e32 v242, 32, v237
	v_add_u32_e32 v243, 64, v243
	v_cmp_lt_i32_e32 vcc, v242, v243
	s_nop 1
	v_cndmask_b32_e32 v242, v237, v242, vcc
	v_lshlrev_b32_e32 v242, 2, v242
	ds_bpermute_b32 v242, v242, v232
	s_waitcnt lgkmcnt(0)
	v_add_f32_e32 v242, v242, v232
	v_frexp_exp_i32_f32_e32 v242, v242
	v_max_i32_e32 v242, 1, v242
	v_add_u32_e32 v242, -1, v242
	v_cvt_f32_u32_e32 v242, v242
	v_exp_f32_e64 v243, -v242
	v_add_f32_e32 v188, v188, v242
	v_xor_b32_e32 v64, 0x80000000, v188
	v_mul_f32_e32 v187, v187, v243
	v_mul_f32_e32 v232, v232, v243
	v_mul_f32_e32 v32, v32, v243
	v_mul_f32_e32 v33, v33, v243
	v_mul_f32_e32 v34, v34, v243
	v_mul_f32_e32 v35, v35, v243
	v_mul_f32_e32 v36, v36, v243
	v_mul_f32_e32 v37, v37, v243
	v_mul_f32_e32 v38, v38, v243
	v_mul_f32_e32 v39, v39, v243
	v_mul_f32_e32 v40, v40, v243
	v_mul_f32_e32 v41, v41, v243
	v_mul_f32_e32 v42, v42, v243
	v_mul_f32_e32 v43, v43, v243
	v_mul_f32_e32 v44, v44, v243
	v_mul_f32_e32 v45, v45, v243
	v_mul_f32_e32 v46, v46, v243
	v_mul_f32_e32 v47, v47, v243
	v_mul_f32_e32 v48, v48, v243
	v_mul_f32_e32 v49, v49, v243
	v_mul_f32_e32 v50, v50, v243
	v_mul_f32_e32 v51, v51, v243
	v_mul_f32_e32 v52, v52, v243
	v_mul_f32_e32 v53, v53, v243
	v_mul_f32_e32 v54, v54, v243
	v_mul_f32_e32 v55, v55, v243
	v_mul_f32_e32 v56, v56, v243
	v_mul_f32_e32 v57, v57, v243
	v_mul_f32_e32 v58, v58, v243
	v_mul_f32_e32 v59, v59, v243
	v_mul_f32_e32 v60, v60, v243
	v_mul_f32_e32 v61, v61, v243
	v_mul_f32_e32 v62, v62, v243
	v_mul_f32_e32 v63, v63, v243
	v_mov_b32_e32 v65, v64
	v_mov_b32_e32 v66, v64
	v_mov_b32_e32 v67, v64
	v_mov_b32_e32 v68, v64
	v_mov_b32_e32 v69, v64
	v_mov_b32_e32 v70, v64
	v_mov_b32_e32 v71, v64
	v_mov_b32_e32 v72, v64
	v_mov_b32_e32 v73, v64
	v_mov_b32_e32 v74, v64
	v_mov_b32_e32 v75, v64
	v_mov_b32_e32 v76, v64
	v_mov_b32_e32 v77, v64
	v_mov_b32_e32 v78, v64
	v_mov_b32_e32 v79, v64
.Lna_nr7:
	v_add_f32_e32 v187, v187, v232
	s_nop 7
	s_nop 7
	s_waitcnt lgkmcnt(0)
	s_barrier
	s_branch .LBB0_273
